# merge hooks/epilogue: drop redundant self-max canonicalize before the 1e-20 clamp (bit-identical for non-sNaN gates)
# speedup vs baseline: 1.0045x; 1.0022x over previous
; __device__ __forceinline__ float fast_rcp(float x) { return __builtin_amdgcn_rcpf(x); }
;     __device__ __forceinline__ void mid(f32x4 (&acc)[2][2][4][2], const Unit& u, int wr, int wc, int fr, int fq, int t) const {
;     ...
;                 const bf16_t* gp = P + (size_t)(row0 + ai * 128 + m * 16) * PS + noff + col0;
; #pragma unroll
;                 for (int bj = 0; bj < 2; ++bj) {
;                     const u32x4 gn = *(const u32x4*)(gp + bj * 128), gd = *(const u32x4*)(gp + bj * 128 + 2048);
;                     f32x4 r0, r1;
;                     r0[0] = bflo(gn.x) * fast_rcp(fmaxf(bflo(gd.x), 1e-20f)); r0[1] = bfhi(gn.x) * fast_rcp(fmaxf(bfhi(gd.x), 1e-20f));
;                     r0[2] = bflo(gn.y) * fast_rcp(fmaxf(bflo(gd.y), 1e-20f)); r0[3] = bfhi(gn.y) * fast_rcp(fmaxf(bfhi(gd.y), 1e-20f));
;                     r1[0] = bflo(gn.z) * fast_rcp(fmaxf(bflo(gd.z), 1e-20f)); r1[1] = bfhi(gn.z) * fast_rcp(fmaxf(bfhi(gd.z), 1e-20f));
;                     r1[2] = bflo(gn.w) * fast_rcp(fmaxf(bflo(gd.w), 1e-20f)); r1[3] = bfhi(gn.w) * fast_rcp(fmaxf(bfhi(gd.w), 1e-20f));
;                     acc[ai][bj][m][0] *= r0; acc[ai][bj][m][1] *= r1;
.LBB0_759:
	s_andn2_b64 vcc, exec, s[6:7]
	s_cbranch_vccnz .LBB0_761
	v_add_u32_e32 v34, s68, v173
	s_cmp_eq_u32 s12, 8
	v_mov_b64_e32 v[36:37], s[42:43]
	s_cselect_b32 s24, s20, 0x4000
	v_mad_i64_i32 v[36:37], vcc, v34, s90, v[36:37]
	s_mov_b32 s5, 0
	v_lshl_add_u64 v[36:37], v[36:37], 0, s[24:25]
	s_movk_i32 s4, 0x800
	v_lshl_add_u64 v[36:37], v[36:37], 0, v[164:165]
	v_lshl_add_u64 v[36:37], v[36:37], 0, s[4:5]
	s_mov_b32 s4, 0x60000
	global_load_dwordx4 v[134:137], v[36:37], off offset:-2048
	global_load_dwordx4 v[138:141], v[36:37], off offset:2048
	global_load_dwordx4 v[178:181], v[36:37], off offset:-1792
	global_load_dwordx4 v[182:185], v[36:37], off offset:2304
	v_lshl_add_u64 v[36:37], v[36:37], 0, s[4:5]
	global_load_dwordx4 v[186:189], v[36:37], off offset:-2048
	global_load_dwordx4 v[190:193], v[36:37], off offset:2048
	global_load_dwordx4 v[194:197], v[36:37], off offset:-1792
	global_load_dwordx4 v[198:201], v[36:37], off offset:2304
	v_lshl_add_u64 v[36:37], v[36:37], 0, s[4:5]
	global_load_dwordx4 v[202:205], v[36:37], off offset:-2048
	global_load_dwordx4 v[206:209], v[36:37], off offset:2048
	global_load_dwordx4 v[210:213], v[36:37], off offset:-1792
	global_load_dwordx4 v[214:217], v[36:37], off offset:2304
	v_lshl_add_u64 v[36:37], v[36:37], 0, s[4:5]
	global_load_dwordx4 v[218:221], v[36:37], off offset:-2048
	global_load_dwordx4 v[222:225], v[36:37], off offset:2048
	global_load_dwordx4 v[226:229], v[36:37], off offset:-1792
	global_load_dwordx4 v[230:233], v[36:37], off offset:2304
	v_lshl_add_u64 v[36:37], v[36:37], 0, s[4:5]
	s_mov_b32 s4, 0x180000
	v_lshl_add_u64 v[36:37], v[36:37], 0, s[4:5]
	s_mov_b32 s4, 0x60000
	s_waitcnt vmcnt(14)
	v_lshlrev_b32_e32 v248, 16, v138
	v_and_b32_e32 v249, 0xffff0000, v138
	v_lshlrev_b32_e32 v250, 16, v139
	v_and_b32_e32 v251, 0xffff0000, v139
	v_max_f32_e32 v248, 0x1e3ce508, v248
	v_max_f32_e32 v249, 0x1e3ce508, v249
	v_max_f32_e32 v250, 0x1e3ce508, v250
	v_max_f32_e32 v251, 0x1e3ce508, v251
	v_rcp_f32_e32 v248, v248
	v_rcp_f32_e32 v249, v249
	v_rcp_f32_e32 v250, v250
	v_rcp_f32_e32 v251, v251
	v_lshlrev_b32_e32 v252, 16, v134
	v_and_b32_e32 v253, 0xffff0000, v134
	v_lshlrev_b32_e32 v254, 16, v135
	v_and_b32_e32 v255, 0xffff0000, v135
	v_pk_mul_f32 v[248:249], v[248:249], v[252:253]
	v_pk_mul_f32 v[250:251], v[250:251], v[254:255]
	v_pk_mul_f32 v[130:131], v[130:131], v[248:249]
	v_pk_mul_f32 v[132:133], v[132:133], v[250:251]
	v_lshlrev_b32_e32 v248, 16, v140
	v_and_b32_e32 v249, 0xffff0000, v140
	v_lshlrev_b32_e32 v250, 16, v141
	v_and_b32_e32 v251, 0xffff0000, v141
	v_max_f32_e32 v248, 0x1e3ce508, v248
	v_max_f32_e32 v249, 0x1e3ce508, v249
	v_max_f32_e32 v250, 0x1e3ce508, v250
	v_max_f32_e32 v251, 0x1e3ce508, v251
	v_rcp_f32_e32 v248, v248
	v_rcp_f32_e32 v249, v249
	v_rcp_f32_e32 v250, v250
	v_rcp_f32_e32 v251, v251
	v_lshlrev_b32_e32 v252, 16, v136
	v_and_b32_e32 v253, 0xffff0000, v136
	v_lshlrev_b32_e32 v254, 16, v137
	v_and_b32_e32 v255, 0xffff0000, v137
	v_pk_mul_f32 v[248:249], v[248:249], v[252:253]
	v_pk_mul_f32 v[250:251], v[250:251], v[254:255]
	v_pk_mul_f32 v[126:127], v[126:127], v[248:249]
	v_pk_mul_f32 v[128:129], v[128:129], v[250:251]
	global_load_dwordx4 v[134:137], v[36:37], off offset:-2048
	global_load_dwordx4 v[138:141], v[36:37], off offset:2048
	s_waitcnt vmcnt(14)
	v_lshlrev_b32_e32 v248, 16, v182
	v_and_b32_e32 v249, 0xffff0000, v182
	v_lshlrev_b32_e32 v250, 16, v183
	v_and_b32_e32 v251, 0xffff0000, v183
	v_max_f32_e32 v248, 0x1e3ce508, v248
	v_max_f32_e32 v249, 0x1e3ce508, v249
	v_max_f32_e32 v250, 0x1e3ce508, v250
	v_max_f32_e32 v251, 0x1e3ce508, v251
	v_rcp_f32_e32 v248, v248
	v_rcp_f32_e32 v249, v249
	v_rcp_f32_e32 v250, v250
	v_rcp_f32_e32 v251, v251
	v_lshlrev_b32_e32 v252, 16, v178
	v_and_b32_e32 v253, 0xffff0000, v178
	v_lshlrev_b32_e32 v254, 16, v179
	v_and_b32_e32 v255, 0xffff0000, v179
	v_pk_mul_f32 v[248:249], v[248:249], v[252:253]
	v_pk_mul_f32 v[250:251], v[250:251], v[254:255]
	v_pk_mul_f32 v[122:123], v[122:123], v[248:249]
	v_pk_mul_f32 v[124:125], v[124:125], v[250:251]
	v_lshlrev_b32_e32 v248, 16, v184
	v_and_b32_e32 v249, 0xffff0000, v184
	v_lshlrev_b32_e32 v250, 16, v185
	v_and_b32_e32 v251, 0xffff0000, v185
	v_max_f32_e32 v248, 0x1e3ce508, v248
	v_max_f32_e32 v249, 0x1e3ce508, v249
	v_max_f32_e32 v250, 0x1e3ce508, v250
	v_max_f32_e32 v251, 0x1e3ce508, v251
	v_rcp_f32_e32 v248, v248
	v_rcp_f32_e32 v249, v249
	v_rcp_f32_e32 v250, v250
	v_rcp_f32_e32 v251, v251
	v_lshlrev_b32_e32 v252, 16, v180
	v_and_b32_e32 v253, 0xffff0000, v180
	v_lshlrev_b32_e32 v254, 16, v181
	v_and_b32_e32 v255, 0xffff0000, v181
	v_pk_mul_f32 v[248:249], v[248:249], v[252:253]
	v_pk_mul_f32 v[250:251], v[250:251], v[254:255]
	v_pk_mul_f32 v[118:119], v[118:119], v[248:249]
	v_pk_mul_f32 v[120:121], v[120:121], v[250:251]
	global_load_dwordx4 v[178:181], v[36:37], off offset:-1792
	global_load_dwordx4 v[182:185], v[36:37], off offset:2304
	v_lshl_add_u64 v[36:37], v[36:37], 0, s[4:5]
	s_waitcnt vmcnt(14)
; __device__ __forceinline__ float fast_rcp(float x) { return __builtin_amdgcn_rcpf(x); }
;     __device__ __forceinline__ void mid(f32x4 (&acc)[2][2][4][2], const Unit& u, int wr, int wc, int fr, int fq, int t) const {
;     ...
;                 const bf16_t* gp = P + (size_t)(row0 + ai * 128 + m * 16) * PS + noff + col0;
; #pragma unroll
;                 for (int bj = 0; bj < 2; ++bj) {
;                     const u32x4 gn = *(const u32x4*)(gp + bj * 128), gd = *(const u32x4*)(gp + bj * 128 + 2048);
;                     f32x4 r0, r1;
;                     r0[0] = bflo(gn.x) * fast_rcp(fmaxf(bflo(gd.x), 1e-20f)); r0[1] = bfhi(gn.x) * fast_rcp(fmaxf(bfhi(gd.x), 1e-20f));
;                     r0[2] = bflo(gn.y) * fast_rcp(fmaxf(bflo(gd.y), 1e-20f)); r0[3] = bfhi(gn.y) * fast_rcp(fmaxf(bfhi(gd.y), 1e-20f));
;                     r1[0] = bflo(gn.z) * fast_rcp(fmaxf(bflo(gd.z), 1e-20f)); r1[1] = bfhi(gn.z) * fast_rcp(fmaxf(bfhi(gd.z), 1e-20f));
;                     r1[2] = bflo(gn.w) * fast_rcp(fmaxf(bflo(gd.w), 1e-20f)); r1[3] = bfhi(gn.w) * fast_rcp(fmaxf(bfhi(gd.w), 1e-20f));
;                     acc[ai][bj][m][0] *= r0; acc[ai][bj][m][1] *= r1;
	v_lshlrev_b32_e32 v248, 16, v190
	v_and_b32_e32 v249, 0xffff0000, v190
	v_lshlrev_b32_e32 v250, 16, v191
	v_and_b32_e32 v251, 0xffff0000, v191
	v_max_f32_e32 v248, 0x1e3ce508, v248
	v_max_f32_e32 v249, 0x1e3ce508, v249
	v_max_f32_e32 v250, 0x1e3ce508, v250
	v_max_f32_e32 v251, 0x1e3ce508, v251
	v_rcp_f32_e32 v248, v248
	v_rcp_f32_e32 v249, v249
	v_rcp_f32_e32 v250, v250
	v_rcp_f32_e32 v251, v251
	v_lshlrev_b32_e32 v252, 16, v186
	v_and_b32_e32 v253, 0xffff0000, v186
	v_lshlrev_b32_e32 v254, 16, v187
	v_and_b32_e32 v255, 0xffff0000, v187
	v_pk_mul_f32 v[248:249], v[248:249], v[252:253]
	v_pk_mul_f32 v[250:251], v[250:251], v[254:255]
	v_pk_mul_f32 v[114:115], v[114:115], v[248:249]
	v_pk_mul_f32 v[116:117], v[116:117], v[250:251]
	v_lshlrev_b32_e32 v248, 16, v192
	v_and_b32_e32 v249, 0xffff0000, v192
	v_lshlrev_b32_e32 v250, 16, v193
	v_and_b32_e32 v251, 0xffff0000, v193
	v_max_f32_e32 v248, 0x1e3ce508, v248
	v_max_f32_e32 v249, 0x1e3ce508, v249
	v_max_f32_e32 v250, 0x1e3ce508, v250
	v_max_f32_e32 v251, 0x1e3ce508, v251
	v_rcp_f32_e32 v248, v248
	v_rcp_f32_e32 v249, v249
	v_rcp_f32_e32 v250, v250
	v_rcp_f32_e32 v251, v251
	v_lshlrev_b32_e32 v252, 16, v188
	v_and_b32_e32 v253, 0xffff0000, v188
	v_lshlrev_b32_e32 v254, 16, v189
	v_and_b32_e32 v255, 0xffff0000, v189
	v_pk_mul_f32 v[248:249], v[248:249], v[252:253]
	v_pk_mul_f32 v[250:251], v[250:251], v[254:255]
	v_pk_mul_f32 v[110:111], v[110:111], v[248:249]
	v_pk_mul_f32 v[112:113], v[112:113], v[250:251]
	global_load_dwordx4 v[186:189], v[36:37], off offset:-2048
	global_load_dwordx4 v[190:193], v[36:37], off offset:2048
	s_waitcnt vmcnt(14)
	v_lshlrev_b32_e32 v248, 16, v198
	v_and_b32_e32 v249, 0xffff0000, v198
	v_lshlrev_b32_e32 v250, 16, v199
	v_and_b32_e32 v251, 0xffff0000, v199
	v_max_f32_e32 v248, 0x1e3ce508, v248
	v_max_f32_e32 v249, 0x1e3ce508, v249
	v_max_f32_e32 v250, 0x1e3ce508, v250
	v_max_f32_e32 v251, 0x1e3ce508, v251
	v_rcp_f32_e32 v248, v248
	v_rcp_f32_e32 v249, v249
	v_rcp_f32_e32 v250, v250
	v_rcp_f32_e32 v251, v251
	v_lshlrev_b32_e32 v252, 16, v194
	v_and_b32_e32 v253, 0xffff0000, v194
	v_lshlrev_b32_e32 v254, 16, v195
	v_and_b32_e32 v255, 0xffff0000, v195
	v_pk_mul_f32 v[248:249], v[248:249], v[252:253]
	v_pk_mul_f32 v[250:251], v[250:251], v[254:255]
	v_pk_mul_f32 v[106:107], v[106:107], v[248:249]
	v_pk_mul_f32 v[108:109], v[108:109], v[250:251]
	v_lshlrev_b32_e32 v248, 16, v200
	v_and_b32_e32 v249, 0xffff0000, v200
	v_lshlrev_b32_e32 v250, 16, v201
	v_and_b32_e32 v251, 0xffff0000, v201
	v_max_f32_e32 v248, 0x1e3ce508, v248
	v_max_f32_e32 v249, 0x1e3ce508, v249
	v_max_f32_e32 v250, 0x1e3ce508, v250
	v_max_f32_e32 v251, 0x1e3ce508, v251
	v_rcp_f32_e32 v248, v248
	v_rcp_f32_e32 v249, v249
	v_rcp_f32_e32 v250, v250
	v_rcp_f32_e32 v251, v251
	v_lshlrev_b32_e32 v252, 16, v196
	v_and_b32_e32 v253, 0xffff0000, v196
	v_lshlrev_b32_e32 v254, 16, v197
	v_and_b32_e32 v255, 0xffff0000, v197
	v_pk_mul_f32 v[248:249], v[248:249], v[252:253]
	v_pk_mul_f32 v[250:251], v[250:251], v[254:255]
	v_pk_mul_f32 v[102:103], v[102:103], v[248:249]
	v_pk_mul_f32 v[104:105], v[104:105], v[250:251]
	global_load_dwordx4 v[194:197], v[36:37], off offset:-1792
	global_load_dwordx4 v[198:201], v[36:37], off offset:2304
	v_lshl_add_u64 v[36:37], v[36:37], 0, s[4:5]
	s_waitcnt vmcnt(14)
	v_lshlrev_b32_e32 v248, 16, v206
	v_and_b32_e32 v249, 0xffff0000, v206
	v_lshlrev_b32_e32 v250, 16, v207
	v_and_b32_e32 v251, 0xffff0000, v207
	v_max_f32_e32 v248, 0x1e3ce508, v248
	v_max_f32_e32 v249, 0x1e3ce508, v249
	v_max_f32_e32 v250, 0x1e3ce508, v250
	v_max_f32_e32 v251, 0x1e3ce508, v251
	v_rcp_f32_e32 v248, v248
	v_rcp_f32_e32 v249, v249
	v_rcp_f32_e32 v250, v250
	v_rcp_f32_e32 v251, v251
	v_lshlrev_b32_e32 v252, 16, v202
	v_and_b32_e32 v253, 0xffff0000, v202
	v_lshlrev_b32_e32 v254, 16, v203
	v_and_b32_e32 v255, 0xffff0000, v203
	v_pk_mul_f32 v[248:249], v[248:249], v[252:253]
	v_pk_mul_f32 v[250:251], v[250:251], v[254:255]
	v_pk_mul_f32 v[98:99], v[98:99], v[248:249]
	v_pk_mul_f32 v[100:101], v[100:101], v[250:251]
	v_lshlrev_b32_e32 v248, 16, v208
	v_and_b32_e32 v249, 0xffff0000, v208
	v_lshlrev_b32_e32 v250, 16, v209
	v_and_b32_e32 v251, 0xffff0000, v209
	v_max_f32_e32 v248, 0x1e3ce508, v248
	v_max_f32_e32 v249, 0x1e3ce508, v249
	v_max_f32_e32 v250, 0x1e3ce508, v250
	v_max_f32_e32 v251, 0x1e3ce508, v251
	v_rcp_f32_e32 v248, v248
	v_rcp_f32_e32 v249, v249
	v_rcp_f32_e32 v250, v250
	v_rcp_f32_e32 v251, v251
	v_lshlrev_b32_e32 v252, 16, v204
	v_and_b32_e32 v253, 0xffff0000, v204
	v_lshlrev_b32_e32 v254, 16, v205
	v_and_b32_e32 v255, 0xffff0000, v205
	v_pk_mul_f32 v[248:249], v[248:249], v[252:253]
	v_pk_mul_f32 v[250:251], v[250:251], v[254:255]
	v_pk_mul_f32 v[94:95], v[94:95], v[248:249]
	v_pk_mul_f32 v[96:97], v[96:97], v[250:251]
	global_load_dwordx4 v[202:205], v[36:37], off offset:-2048
	global_load_dwordx4 v[206:209], v[36:37], off offset:2048
	s_waitcnt vmcnt(14)
; __device__ __forceinline__ float fast_rcp(float x) { return __builtin_amdgcn_rcpf(x); }
;     __device__ __forceinline__ void mid(f32x4 (&acc)[2][2][4][2], const Unit& u, int wr, int wc, int fr, int fq, int t) const {
;     ...
;                 const bf16_t* gp = P + (size_t)(row0 + ai * 128 + m * 16) * PS + noff + col0;
; #pragma unroll
;                 for (int bj = 0; bj < 2; ++bj) {
;                     const u32x4 gn = *(const u32x4*)(gp + bj * 128), gd = *(const u32x4*)(gp + bj * 128 + 2048);
;                     f32x4 r0, r1;
;                     r0[0] = bflo(gn.x) * fast_rcp(fmaxf(bflo(gd.x), 1e-20f)); r0[1] = bfhi(gn.x) * fast_rcp(fmaxf(bfhi(gd.x), 1e-20f));
;                     r0[2] = bflo(gn.y) * fast_rcp(fmaxf(bflo(gd.y), 1e-20f)); r0[3] = bfhi(gn.y) * fast_rcp(fmaxf(bfhi(gd.y), 1e-20f));
;                     r1[0] = bflo(gn.z) * fast_rcp(fmaxf(bflo(gd.z), 1e-20f)); r1[1] = bfhi(gn.z) * fast_rcp(fmaxf(bfhi(gd.z), 1e-20f));
;                     r1[2] = bflo(gn.w) * fast_rcp(fmaxf(bflo(gd.w), 1e-20f)); r1[3] = bfhi(gn.w) * fast_rcp(fmaxf(bfhi(gd.w), 1e-20f));
;                     acc[ai][bj][m][0] *= r0; acc[ai][bj][m][1] *= r1;
	v_lshlrev_b32_e32 v248, 16, v214
	v_and_b32_e32 v249, 0xffff0000, v214
	v_lshlrev_b32_e32 v250, 16, v215
	v_and_b32_e32 v251, 0xffff0000, v215
	v_max_f32_e32 v248, 0x1e3ce508, v248
	v_max_f32_e32 v249, 0x1e3ce508, v249
	v_max_f32_e32 v250, 0x1e3ce508, v250
	v_max_f32_e32 v251, 0x1e3ce508, v251
	v_rcp_f32_e32 v248, v248
	v_rcp_f32_e32 v249, v249
	v_rcp_f32_e32 v250, v250
	v_rcp_f32_e32 v251, v251
	v_lshlrev_b32_e32 v252, 16, v210
	v_and_b32_e32 v253, 0xffff0000, v210
	v_lshlrev_b32_e32 v254, 16, v211
	v_and_b32_e32 v255, 0xffff0000, v211
	v_pk_mul_f32 v[248:249], v[248:249], v[252:253]
	v_pk_mul_f32 v[250:251], v[250:251], v[254:255]
	v_pk_mul_f32 v[90:91], v[90:91], v[248:249]
	v_pk_mul_f32 v[92:93], v[92:93], v[250:251]
	v_lshlrev_b32_e32 v248, 16, v216
	v_and_b32_e32 v249, 0xffff0000, v216
	v_lshlrev_b32_e32 v250, 16, v217
	v_and_b32_e32 v251, 0xffff0000, v217
	v_max_f32_e32 v248, 0x1e3ce508, v248
	v_max_f32_e32 v249, 0x1e3ce508, v249
	v_max_f32_e32 v250, 0x1e3ce508, v250
	v_max_f32_e32 v251, 0x1e3ce508, v251
	v_rcp_f32_e32 v248, v248
	v_rcp_f32_e32 v249, v249
	v_rcp_f32_e32 v250, v250
	v_rcp_f32_e32 v251, v251
	v_lshlrev_b32_e32 v252, 16, v212
	v_and_b32_e32 v253, 0xffff0000, v212
	v_lshlrev_b32_e32 v254, 16, v213
	v_and_b32_e32 v255, 0xffff0000, v213
	v_pk_mul_f32 v[248:249], v[248:249], v[252:253]
	v_pk_mul_f32 v[250:251], v[250:251], v[254:255]
	v_pk_mul_f32 v[86:87], v[86:87], v[248:249]
	v_pk_mul_f32 v[88:89], v[88:89], v[250:251]
	global_load_dwordx4 v[210:213], v[36:37], off offset:-1792
	global_load_dwordx4 v[214:217], v[36:37], off offset:2304
	v_lshl_add_u64 v[36:37], v[36:37], 0, s[4:5]
	s_waitcnt vmcnt(14)
	v_lshlrev_b32_e32 v248, 16, v222
	v_and_b32_e32 v249, 0xffff0000, v222
	v_lshlrev_b32_e32 v250, 16, v223
	v_and_b32_e32 v251, 0xffff0000, v223
	v_max_f32_e32 v248, 0x1e3ce508, v248
	v_max_f32_e32 v249, 0x1e3ce508, v249
	v_max_f32_e32 v250, 0x1e3ce508, v250
	v_max_f32_e32 v251, 0x1e3ce508, v251
	v_rcp_f32_e32 v248, v248
	v_rcp_f32_e32 v249, v249
	v_rcp_f32_e32 v250, v250
	v_rcp_f32_e32 v251, v251
	v_lshlrev_b32_e32 v252, 16, v218
	v_and_b32_e32 v253, 0xffff0000, v218
	v_lshlrev_b32_e32 v254, 16, v219
	v_and_b32_e32 v255, 0xffff0000, v219
	v_pk_mul_f32 v[248:249], v[248:249], v[252:253]
	v_pk_mul_f32 v[250:251], v[250:251], v[254:255]
	v_pk_mul_f32 v[82:83], v[82:83], v[248:249]
	v_pk_mul_f32 v[84:85], v[84:85], v[250:251]
	v_lshlrev_b32_e32 v248, 16, v224
	v_and_b32_e32 v249, 0xffff0000, v224
	v_lshlrev_b32_e32 v250, 16, v225
	v_and_b32_e32 v251, 0xffff0000, v225
	v_max_f32_e32 v248, 0x1e3ce508, v248
	v_max_f32_e32 v249, 0x1e3ce508, v249
	v_max_f32_e32 v250, 0x1e3ce508, v250
	v_max_f32_e32 v251, 0x1e3ce508, v251
	v_rcp_f32_e32 v248, v248
	v_rcp_f32_e32 v249, v249
	v_rcp_f32_e32 v250, v250
	v_rcp_f32_e32 v251, v251
	v_lshlrev_b32_e32 v252, 16, v220
	v_and_b32_e32 v253, 0xffff0000, v220
	v_lshlrev_b32_e32 v254, 16, v221
	v_and_b32_e32 v255, 0xffff0000, v221
	v_pk_mul_f32 v[248:249], v[248:249], v[252:253]
	v_pk_mul_f32 v[250:251], v[250:251], v[254:255]
	v_pk_mul_f32 v[78:79], v[78:79], v[248:249]
	v_pk_mul_f32 v[80:81], v[80:81], v[250:251]
	global_load_dwordx4 v[218:221], v[36:37], off offset:-2048
	global_load_dwordx4 v[222:225], v[36:37], off offset:2048
	s_waitcnt vmcnt(14)
	v_lshlrev_b32_e32 v248, 16, v230
	v_and_b32_e32 v249, 0xffff0000, v230
	v_lshlrev_b32_e32 v250, 16, v231
	v_and_b32_e32 v251, 0xffff0000, v231
	v_max_f32_e32 v248, 0x1e3ce508, v248
	v_max_f32_e32 v249, 0x1e3ce508, v249
	v_max_f32_e32 v250, 0x1e3ce508, v250
	v_max_f32_e32 v251, 0x1e3ce508, v251
	v_rcp_f32_e32 v248, v248
	v_rcp_f32_e32 v249, v249
	v_rcp_f32_e32 v250, v250
	v_rcp_f32_e32 v251, v251
	v_lshlrev_b32_e32 v252, 16, v226
	v_and_b32_e32 v253, 0xffff0000, v226
	v_lshlrev_b32_e32 v254, 16, v227
	v_and_b32_e32 v255, 0xffff0000, v227
	v_pk_mul_f32 v[248:249], v[248:249], v[252:253]
	v_pk_mul_f32 v[250:251], v[250:251], v[254:255]
	v_pk_mul_f32 v[74:75], v[74:75], v[248:249]
	v_pk_mul_f32 v[76:77], v[76:77], v[250:251]
	v_lshlrev_b32_e32 v248, 16, v232
	v_and_b32_e32 v249, 0xffff0000, v232
	v_lshlrev_b32_e32 v250, 16, v233
	v_and_b32_e32 v251, 0xffff0000, v233
	v_max_f32_e32 v248, 0x1e3ce508, v248
	v_max_f32_e32 v249, 0x1e3ce508, v249
	v_max_f32_e32 v250, 0x1e3ce508, v250
	v_max_f32_e32 v251, 0x1e3ce508, v251
	v_rcp_f32_e32 v248, v248
	v_rcp_f32_e32 v249, v249
	v_rcp_f32_e32 v250, v250
	v_rcp_f32_e32 v251, v251
	v_lshlrev_b32_e32 v252, 16, v228
	v_and_b32_e32 v253, 0xffff0000, v228
	v_lshlrev_b32_e32 v254, 16, v229
	v_and_b32_e32 v255, 0xffff0000, v229
	v_pk_mul_f32 v[248:249], v[248:249], v[252:253]
	v_pk_mul_f32 v[250:251], v[250:251], v[254:255]
	v_pk_mul_f32 v[70:71], v[70:71], v[248:249]
	v_pk_mul_f32 v[72:73], v[72:73], v[250:251]
	global_load_dwordx4 v[226:229], v[36:37], off offset:-1792
	global_load_dwordx4 v[230:233], v[36:37], off offset:2304
	v_lshl_add_u64 v[36:37], v[36:37], 0, s[4:5]
	s_waitcnt vmcnt(14)
; __device__ __forceinline__ float fast_rcp(float x) { return __builtin_amdgcn_rcpf(x); }
;     __device__ __forceinline__ void mid(f32x4 (&acc)[2][2][4][2], const Unit& u, int wr, int wc, int fr, int fq, int t) const {
;     ...
;                 const bf16_t* gp = P + (size_t)(row0 + ai * 128 + m * 16) * PS + noff + col0;
; #pragma unroll
;                 for (int bj = 0; bj < 2; ++bj) {
;                     const u32x4 gn = *(const u32x4*)(gp + bj * 128), gd = *(const u32x4*)(gp + bj * 128 + 2048);
;                     f32x4 r0, r1;
;                     r0[0] = bflo(gn.x) * fast_rcp(fmaxf(bflo(gd.x), 1e-20f)); r0[1] = bfhi(gn.x) * fast_rcp(fmaxf(bfhi(gd.x), 1e-20f));
;                     r0[2] = bflo(gn.y) * fast_rcp(fmaxf(bflo(gd.y), 1e-20f)); r0[3] = bfhi(gn.y) * fast_rcp(fmaxf(bfhi(gd.y), 1e-20f));
;                     r1[0] = bflo(gn.z) * fast_rcp(fmaxf(bflo(gd.z), 1e-20f)); r1[1] = bfhi(gn.z) * fast_rcp(fmaxf(bfhi(gd.z), 1e-20f));
;                     r1[2] = bflo(gn.w) * fast_rcp(fmaxf(bflo(gd.w), 1e-20f)); r1[3] = bfhi(gn.w) * fast_rcp(fmaxf(bfhi(gd.w), 1e-20f));
;                     acc[ai][bj][m][0] *= r0; acc[ai][bj][m][1] *= r1;
	v_lshlrev_b32_e32 v248, 16, v138
	v_and_b32_e32 v249, 0xffff0000, v138
	v_lshlrev_b32_e32 v250, 16, v139
	v_and_b32_e32 v251, 0xffff0000, v139
	v_max_f32_e32 v248, 0x1e3ce508, v248
	v_max_f32_e32 v249, 0x1e3ce508, v249
	v_max_f32_e32 v250, 0x1e3ce508, v250
	v_max_f32_e32 v251, 0x1e3ce508, v251
	v_rcp_f32_e32 v248, v248
	v_rcp_f32_e32 v249, v249
	v_rcp_f32_e32 v250, v250
	v_rcp_f32_e32 v251, v251
	v_lshlrev_b32_e32 v252, 16, v134
	v_and_b32_e32 v253, 0xffff0000, v134
	v_lshlrev_b32_e32 v254, 16, v135
	v_and_b32_e32 v255, 0xffff0000, v135
	v_pk_mul_f32 v[248:249], v[248:249], v[252:253]
	v_pk_mul_f32 v[250:251], v[250:251], v[254:255]
	v_pk_mul_f32 v[66:67], v[66:67], v[248:249]
	v_pk_mul_f32 v[68:69], v[68:69], v[250:251]
	v_lshlrev_b32_e32 v248, 16, v140
	v_and_b32_e32 v249, 0xffff0000, v140
	v_lshlrev_b32_e32 v250, 16, v141
	v_and_b32_e32 v251, 0xffff0000, v141
	v_max_f32_e32 v248, 0x1e3ce508, v248
	v_max_f32_e32 v249, 0x1e3ce508, v249
	v_max_f32_e32 v250, 0x1e3ce508, v250
	v_max_f32_e32 v251, 0x1e3ce508, v251
	v_rcp_f32_e32 v248, v248
	v_rcp_f32_e32 v249, v249
	v_rcp_f32_e32 v250, v250
	v_rcp_f32_e32 v251, v251
	v_lshlrev_b32_e32 v252, 16, v136
	v_and_b32_e32 v253, 0xffff0000, v136
	v_lshlrev_b32_e32 v254, 16, v137
	v_and_b32_e32 v255, 0xffff0000, v137
	v_pk_mul_f32 v[248:249], v[248:249], v[252:253]
	v_pk_mul_f32 v[250:251], v[250:251], v[254:255]
	v_pk_mul_f32 v[62:63], v[62:63], v[248:249]
	v_pk_mul_f32 v[64:65], v[64:65], v[250:251]
	s_waitcnt vmcnt(12)
	v_lshlrev_b32_e32 v248, 16, v182
	v_and_b32_e32 v249, 0xffff0000, v182
	v_lshlrev_b32_e32 v250, 16, v183
	v_and_b32_e32 v251, 0xffff0000, v183
	v_max_f32_e32 v248, 0x1e3ce508, v248
	v_max_f32_e32 v249, 0x1e3ce508, v249
	v_max_f32_e32 v250, 0x1e3ce508, v250
	v_max_f32_e32 v251, 0x1e3ce508, v251
	v_rcp_f32_e32 v248, v248
	v_rcp_f32_e32 v249, v249
	v_rcp_f32_e32 v250, v250
	v_rcp_f32_e32 v251, v251
	v_lshlrev_b32_e32 v252, 16, v178
	v_and_b32_e32 v253, 0xffff0000, v178
	v_lshlrev_b32_e32 v254, 16, v179
	v_and_b32_e32 v255, 0xffff0000, v179
	v_pk_mul_f32 v[248:249], v[248:249], v[252:253]
	v_pk_mul_f32 v[250:251], v[250:251], v[254:255]
	v_pk_mul_f32 v[58:59], v[58:59], v[248:249]
	v_pk_mul_f32 v[60:61], v[60:61], v[250:251]
	v_lshlrev_b32_e32 v248, 16, v184
	v_and_b32_e32 v249, 0xffff0000, v184
	v_lshlrev_b32_e32 v250, 16, v185
	v_and_b32_e32 v251, 0xffff0000, v185
	v_max_f32_e32 v248, 0x1e3ce508, v248
	v_max_f32_e32 v249, 0x1e3ce508, v249
	v_max_f32_e32 v250, 0x1e3ce508, v250
	v_max_f32_e32 v251, 0x1e3ce508, v251
	v_rcp_f32_e32 v248, v248
	v_rcp_f32_e32 v249, v249
	v_rcp_f32_e32 v250, v250
	v_rcp_f32_e32 v251, v251
	v_lshlrev_b32_e32 v252, 16, v180
	v_and_b32_e32 v253, 0xffff0000, v180
	v_lshlrev_b32_e32 v254, 16, v181
	v_and_b32_e32 v255, 0xffff0000, v181
	v_pk_mul_f32 v[248:249], v[248:249], v[252:253]
	v_pk_mul_f32 v[250:251], v[250:251], v[254:255]
	v_pk_mul_f32 v[54:55], v[54:55], v[248:249]
	v_pk_mul_f32 v[56:57], v[56:57], v[250:251]
	s_waitcnt vmcnt(10)
	v_lshlrev_b32_e32 v248, 16, v190
	v_and_b32_e32 v249, 0xffff0000, v190
	v_lshlrev_b32_e32 v250, 16, v191
	v_and_b32_e32 v251, 0xffff0000, v191
	v_max_f32_e32 v248, 0x1e3ce508, v248
	v_max_f32_e32 v249, 0x1e3ce508, v249
	v_max_f32_e32 v250, 0x1e3ce508, v250
	v_max_f32_e32 v251, 0x1e3ce508, v251
	v_rcp_f32_e32 v248, v248
	v_rcp_f32_e32 v249, v249
	v_rcp_f32_e32 v250, v250
	v_rcp_f32_e32 v251, v251
	v_lshlrev_b32_e32 v252, 16, v186
	v_and_b32_e32 v253, 0xffff0000, v186
	v_lshlrev_b32_e32 v254, 16, v187
	v_and_b32_e32 v255, 0xffff0000, v187
	v_pk_mul_f32 v[248:249], v[248:249], v[252:253]
	v_pk_mul_f32 v[250:251], v[250:251], v[254:255]
	v_pk_mul_f32 v[50:51], v[50:51], v[248:249]
	v_pk_mul_f32 v[52:53], v[52:53], v[250:251]
	v_lshlrev_b32_e32 v248, 16, v192
	v_and_b32_e32 v249, 0xffff0000, v192
	v_lshlrev_b32_e32 v250, 16, v193
	v_and_b32_e32 v251, 0xffff0000, v193
	v_max_f32_e32 v248, 0x1e3ce508, v248
	v_max_f32_e32 v249, 0x1e3ce508, v249
	v_max_f32_e32 v250, 0x1e3ce508, v250
	v_max_f32_e32 v251, 0x1e3ce508, v251
	v_rcp_f32_e32 v248, v248
	v_rcp_f32_e32 v249, v249
	v_rcp_f32_e32 v250, v250
	v_rcp_f32_e32 v251, v251
	v_lshlrev_b32_e32 v252, 16, v188
	v_and_b32_e32 v253, 0xffff0000, v188
	v_lshlrev_b32_e32 v254, 16, v189
	v_and_b32_e32 v255, 0xffff0000, v189
	v_pk_mul_f32 v[248:249], v[248:249], v[252:253]
	v_pk_mul_f32 v[250:251], v[250:251], v[254:255]
	v_pk_mul_f32 v[46:47], v[46:47], v[248:249]
	v_pk_mul_f32 v[48:49], v[48:49], v[250:251]
	s_waitcnt vmcnt(8)
	v_lshlrev_b32_e32 v248, 16, v198
	v_and_b32_e32 v249, 0xffff0000, v198
	v_lshlrev_b32_e32 v250, 16, v199
	v_and_b32_e32 v251, 0xffff0000, v199
	v_max_f32_e32 v248, 0x1e3ce508, v248
	v_max_f32_e32 v249, 0x1e3ce508, v249
	v_max_f32_e32 v250, 0x1e3ce508, v250
	v_max_f32_e32 v251, 0x1e3ce508, v251
	v_rcp_f32_e32 v248, v248
	v_rcp_f32_e32 v249, v249
	v_rcp_f32_e32 v250, v250
	v_rcp_f32_e32 v251, v251
	v_lshlrev_b32_e32 v252, 16, v194
	v_and_b32_e32 v253, 0xffff0000, v194
	v_lshlrev_b32_e32 v254, 16, v195
	v_and_b32_e32 v255, 0xffff0000, v195
	v_pk_mul_f32 v[248:249], v[248:249], v[252:253]
	v_pk_mul_f32 v[250:251], v[250:251], v[254:255]
	v_pk_mul_f32 v[42:43], v[42:43], v[248:249]
	v_pk_mul_f32 v[44:45], v[44:45], v[250:251]
	v_lshlrev_b32_e32 v248, 16, v200
	v_and_b32_e32 v249, 0xffff0000, v200
	v_lshlrev_b32_e32 v250, 16, v201
	v_and_b32_e32 v251, 0xffff0000, v201
	v_max_f32_e32 v248, 0x1e3ce508, v248
	v_max_f32_e32 v249, 0x1e3ce508, v249
	v_max_f32_e32 v250, 0x1e3ce508, v250
	v_max_f32_e32 v251, 0x1e3ce508, v251
	v_rcp_f32_e32 v248, v248
	v_rcp_f32_e32 v249, v249
	v_rcp_f32_e32 v250, v250
	v_rcp_f32_e32 v251, v251
	v_lshlrev_b32_e32 v252, 16, v196
	v_and_b32_e32 v253, 0xffff0000, v196
	v_lshlrev_b32_e32 v254, 16, v197
	v_and_b32_e32 v255, 0xffff0000, v197
	v_pk_mul_f32 v[248:249], v[248:249], v[252:253]
	v_pk_mul_f32 v[250:251], v[250:251], v[254:255]
	v_pk_mul_f32 v[38:39], v[38:39], v[248:249]
	v_pk_mul_f32 v[40:41], v[40:41], v[250:251]
	s_waitcnt vmcnt(6)
; __device__ __forceinline__ float fast_rcp(float x) { return __builtin_amdgcn_rcpf(x); }
;     __device__ __forceinline__ void mid(f32x4 (&acc)[2][2][4][2], const Unit& u, int wr, int wc, int fr, int fq, int t) const {
;     ...
;                 const bf16_t* gp = P + (size_t)(row0 + ai * 128 + m * 16) * PS + noff + col0;
; #pragma unroll
;                 for (int bj = 0; bj < 2; ++bj) {
;                     const u32x4 gn = *(const u32x4*)(gp + bj * 128), gd = *(const u32x4*)(gp + bj * 128 + 2048);
;                     f32x4 r0, r1;
;                     r0[0] = bflo(gn.x) * fast_rcp(fmaxf(bflo(gd.x), 1e-20f)); r0[1] = bfhi(gn.x) * fast_rcp(fmaxf(bfhi(gd.x), 1e-20f));
;                     r0[2] = bflo(gn.y) * fast_rcp(fmaxf(bflo(gd.y), 1e-20f)); r0[3] = bfhi(gn.y) * fast_rcp(fmaxf(bfhi(gd.y), 1e-20f));
;                     r1[0] = bflo(gn.z) * fast_rcp(fmaxf(bflo(gd.z), 1e-20f)); r1[1] = bfhi(gn.z) * fast_rcp(fmaxf(bfhi(gd.z), 1e-20f));
;                     r1[2] = bflo(gn.w) * fast_rcp(fmaxf(bflo(gd.w), 1e-20f)); r1[3] = bfhi(gn.w) * fast_rcp(fmaxf(bfhi(gd.w), 1e-20f));
;                     acc[ai][bj][m][0] *= r0; acc[ai][bj][m][1] *= r1;
	v_lshlrev_b32_e32 v248, 16, v206
	v_and_b32_e32 v249, 0xffff0000, v206
	v_lshlrev_b32_e32 v250, 16, v207
	v_and_b32_e32 v251, 0xffff0000, v207
	v_max_f32_e32 v248, 0x1e3ce508, v248
	v_max_f32_e32 v249, 0x1e3ce508, v249
	v_max_f32_e32 v250, 0x1e3ce508, v250
	v_max_f32_e32 v251, 0x1e3ce508, v251
	v_rcp_f32_e32 v248, v248
	v_rcp_f32_e32 v249, v249
	v_rcp_f32_e32 v250, v250
	v_rcp_f32_e32 v251, v251
	v_lshlrev_b32_e32 v252, 16, v202
	v_and_b32_e32 v253, 0xffff0000, v202
	v_lshlrev_b32_e32 v254, 16, v203
	v_and_b32_e32 v255, 0xffff0000, v203
	v_pk_mul_f32 v[248:249], v[248:249], v[252:253]
	v_pk_mul_f32 v[250:251], v[250:251], v[254:255]
	v_pk_mul_f32 v[28:29], v[28:29], v[248:249]
	v_pk_mul_f32 v[30:31], v[30:31], v[250:251]
	v_lshlrev_b32_e32 v248, 16, v208
	v_and_b32_e32 v249, 0xffff0000, v208
	v_lshlrev_b32_e32 v250, 16, v209
	v_and_b32_e32 v251, 0xffff0000, v209
	v_max_f32_e32 v248, 0x1e3ce508, v248
	v_max_f32_e32 v249, 0x1e3ce508, v249
	v_max_f32_e32 v250, 0x1e3ce508, v250
	v_max_f32_e32 v251, 0x1e3ce508, v251
	v_rcp_f32_e32 v248, v248
	v_rcp_f32_e32 v249, v249
	v_rcp_f32_e32 v250, v250
	v_rcp_f32_e32 v251, v251
	v_lshlrev_b32_e32 v252, 16, v204
	v_and_b32_e32 v253, 0xffff0000, v204
	v_lshlrev_b32_e32 v254, 16, v205
	v_and_b32_e32 v255, 0xffff0000, v205
	v_pk_mul_f32 v[248:249], v[248:249], v[252:253]
	v_pk_mul_f32 v[250:251], v[250:251], v[254:255]
	v_pk_mul_f32 v[24:25], v[24:25], v[248:249]
	v_pk_mul_f32 v[26:27], v[26:27], v[250:251]
	s_waitcnt vmcnt(4)
	v_lshlrev_b32_e32 v248, 16, v214
	v_and_b32_e32 v249, 0xffff0000, v214
	v_lshlrev_b32_e32 v250, 16, v215
	v_and_b32_e32 v251, 0xffff0000, v215
	v_max_f32_e32 v248, 0x1e3ce508, v248
	v_max_f32_e32 v249, 0x1e3ce508, v249
	v_max_f32_e32 v250, 0x1e3ce508, v250
	v_max_f32_e32 v251, 0x1e3ce508, v251
	v_rcp_f32_e32 v248, v248
	v_rcp_f32_e32 v249, v249
	v_rcp_f32_e32 v250, v250
	v_rcp_f32_e32 v251, v251
	v_lshlrev_b32_e32 v252, 16, v210
	v_and_b32_e32 v253, 0xffff0000, v210
	v_lshlrev_b32_e32 v254, 16, v211
	v_and_b32_e32 v255, 0xffff0000, v211
	v_pk_mul_f32 v[248:249], v[248:249], v[252:253]
	v_pk_mul_f32 v[250:251], v[250:251], v[254:255]
	v_pk_mul_f32 v[20:21], v[20:21], v[248:249]
	v_pk_mul_f32 v[22:23], v[22:23], v[250:251]
	v_lshlrev_b32_e32 v248, 16, v216
	v_and_b32_e32 v249, 0xffff0000, v216
	v_lshlrev_b32_e32 v250, 16, v217
	v_and_b32_e32 v251, 0xffff0000, v217
	v_max_f32_e32 v248, 0x1e3ce508, v248
	v_max_f32_e32 v249, 0x1e3ce508, v249
	v_max_f32_e32 v250, 0x1e3ce508, v250
	v_max_f32_e32 v251, 0x1e3ce508, v251
	v_rcp_f32_e32 v248, v248
	v_rcp_f32_e32 v249, v249
	v_rcp_f32_e32 v250, v250
	v_rcp_f32_e32 v251, v251
	v_lshlrev_b32_e32 v252, 16, v212
	v_and_b32_e32 v253, 0xffff0000, v212
	v_lshlrev_b32_e32 v254, 16, v213
	v_and_b32_e32 v255, 0xffff0000, v213
	v_pk_mul_f32 v[248:249], v[248:249], v[252:253]
	v_pk_mul_f32 v[250:251], v[250:251], v[254:255]
	v_pk_mul_f32 v[16:17], v[16:17], v[248:249]
	v_pk_mul_f32 v[18:19], v[18:19], v[250:251]
	s_waitcnt vmcnt(2)
	v_lshlrev_b32_e32 v248, 16, v222
	v_and_b32_e32 v249, 0xffff0000, v222
	v_lshlrev_b32_e32 v250, 16, v223
	v_and_b32_e32 v251, 0xffff0000, v223
	v_max_f32_e32 v248, 0x1e3ce508, v248
	v_max_f32_e32 v249, 0x1e3ce508, v249
	v_max_f32_e32 v250, 0x1e3ce508, v250
	v_max_f32_e32 v251, 0x1e3ce508, v251
	v_rcp_f32_e32 v248, v248
	v_rcp_f32_e32 v249, v249
	v_rcp_f32_e32 v250, v250
	v_rcp_f32_e32 v251, v251
	v_lshlrev_b32_e32 v252, 16, v218
	v_and_b32_e32 v253, 0xffff0000, v218
	v_lshlrev_b32_e32 v254, 16, v219
	v_and_b32_e32 v255, 0xffff0000, v219
	v_pk_mul_f32 v[248:249], v[248:249], v[252:253]
	v_pk_mul_f32 v[250:251], v[250:251], v[254:255]
	v_pk_mul_f32 v[12:13], v[12:13], v[248:249]
	v_pk_mul_f32 v[14:15], v[14:15], v[250:251]
	v_lshlrev_b32_e32 v248, 16, v224
	v_and_b32_e32 v249, 0xffff0000, v224
	v_lshlrev_b32_e32 v250, 16, v225
	v_and_b32_e32 v251, 0xffff0000, v225
	v_max_f32_e32 v248, 0x1e3ce508, v248
	v_max_f32_e32 v249, 0x1e3ce508, v249
	v_max_f32_e32 v250, 0x1e3ce508, v250
	v_max_f32_e32 v251, 0x1e3ce508, v251
	v_rcp_f32_e32 v248, v248
	v_rcp_f32_e32 v249, v249
	v_rcp_f32_e32 v250, v250
	v_rcp_f32_e32 v251, v251
	v_lshlrev_b32_e32 v252, 16, v220
	v_and_b32_e32 v253, 0xffff0000, v220
	v_lshlrev_b32_e32 v254, 16, v221
	v_and_b32_e32 v255, 0xffff0000, v221
	v_pk_mul_f32 v[248:249], v[248:249], v[252:253]
	v_pk_mul_f32 v[250:251], v[250:251], v[254:255]
	v_pk_mul_f32 v[8:9], v[8:9], v[248:249]
	v_pk_mul_f32 v[10:11], v[10:11], v[250:251]
	s_waitcnt vmcnt(0)
	v_lshlrev_b32_e32 v248, 16, v230
	v_and_b32_e32 v249, 0xffff0000, v230
	v_lshlrev_b32_e32 v250, 16, v231
	v_and_b32_e32 v251, 0xffff0000, v231
	v_max_f32_e32 v248, 0x1e3ce508, v248
	v_max_f32_e32 v249, 0x1e3ce508, v249
	v_max_f32_e32 v250, 0x1e3ce508, v250
	v_max_f32_e32 v251, 0x1e3ce508, v251
	v_rcp_f32_e32 v248, v248
	v_rcp_f32_e32 v249, v249
	v_rcp_f32_e32 v250, v250
	v_rcp_f32_e32 v251, v251
	v_lshlrev_b32_e32 v252, 16, v226
	v_and_b32_e32 v253, 0xffff0000, v226
	v_lshlrev_b32_e32 v254, 16, v227
	v_and_b32_e32 v255, 0xffff0000, v227
	v_pk_mul_f32 v[248:249], v[248:249], v[252:253]
	v_pk_mul_f32 v[250:251], v[250:251], v[254:255]
	v_pk_mul_f32 v[4:5], v[4:5], v[248:249]
	v_pk_mul_f32 v[6:7], v[6:7], v[250:251]
	v_lshlrev_b32_e32 v248, 16, v232
	v_and_b32_e32 v249, 0xffff0000, v232
	v_lshlrev_b32_e32 v250, 16, v233
	v_and_b32_e32 v251, 0xffff0000, v233
	v_max_f32_e32 v248, 0x1e3ce508, v248
	v_max_f32_e32 v249, 0x1e3ce508, v249
	v_max_f32_e32 v250, 0x1e3ce508, v250
	v_max_f32_e32 v251, 0x1e3ce508, v251
	v_rcp_f32_e32 v248, v248
	v_rcp_f32_e32 v249, v249
	v_rcp_f32_e32 v250, v250
	v_rcp_f32_e32 v251, v251
	v_lshlrev_b32_e32 v252, 16, v228
	v_and_b32_e32 v253, 0xffff0000, v228
	v_lshlrev_b32_e32 v254, 16, v229
	v_and_b32_e32 v255, 0xffff0000, v229
	v_pk_mul_f32 v[248:249], v[248:249], v[252:253]
	v_pk_mul_f32 v[250:251], v[250:251], v[254:255]
	v_pk_mul_f32 v[0:1], v[0:1], v[248:249]
	v_pk_mul_f32 v[2:3], v[2:3], v[250:251]

; __device__ __forceinline__ unsigned pk2(float lo, float hi) { f32x2 v = {lo, hi}; bf16x2_t b = __builtin_convertvector(v, bf16x2_t); return __builtin_bit_cast(unsigned, b); }
;     __device__ __forceinline__ void operator()(const f32x4 (&acc)[2][2][4][2], const Unit& u, int wr, int wc, int fr, int fq) const {
;     ...
;                 const size_t row = (size_t)(row0 + ai * 128 + m * 16);
; #pragma unroll
;                 for (int bj = 0; bj < 2; ++bj) {
;                     const int col = col0 + bj * 128;
;                     const u32x4 g = *(const u32x4*)(P + row * PS + C_GATE + 4096 + col);
;                     f32x4 v0 = acc[ai][bj][m][0], v1 = acc[ai][bj][m][1];
;                     v0[0] *= fmaxf(bflo(g.x), 1e-20f); v0[1] *= fmaxf(bfhi(g.x), 1e-20f); v0[2] *= fmaxf(bflo(g.y), 1e-20f); v0[3] *= fmaxf(bfhi(g.y), 1e-20f);
;                     v1[0] *= fmaxf(bflo(g.z), 1e-20f); v1[1] *= fmaxf(bfhi(g.z), 1e-20f); v1[2] *= fmaxf(bflo(g.w), 1e-20f); v1[3] *= fmaxf(bfhi(g.w), 1e-20f);
;                     u32x4 w; w.x = pk2(v0[0], v0[1]); w.y = pk2(v0[2], v0[3]); w.z = pk2(v1[0], v1[1]); w.w = pk2(v1[2], v1[3]);
;                     *(u32x4*)(Yb + row * DM + col) = w;
.LBB0_766:
	v_lshl_add_u32 v34, s18, 8, v174
	v_mov_b64_e32 v[36:37], s[42:43]
	v_ashrrev_i32_e32 v159, 31, v158
	v_mad_i64_i32 v[36:37], vcc, v34, s90, v[36:37]
	v_lshlrev_b64 v[160:161], 1, v[158:159]
	v_lshl_add_u64 v[36:37], v[36:37], 0, s[36:37]
	v_mov_b32_e32 v164, v34
	v_ashrrev_i32_e32 v165, 31, v34
	v_lshl_add_u64 v[36:37], v[36:37], 0, v[160:161]
	v_lshlrev_b64 v[164:165], 12, v[164:165]
	v_lshl_add_u64 v[162:163], s[40:41], 0, v[164:165]
	v_lshl_add_u64 v[162:163], v[162:163], 0, v[160:161]
	s_mov_b32 s4, 0x60000
	s_mov_b32 s5, 0
	global_load_dwordx4 v[134:137], v[36:37], off
	global_load_dwordx4 v[138:141], v[36:37], off offset:256
	v_lshl_add_u64 v[36:37], v[36:37], 0, s[4:5]
	global_load_dwordx4 v[178:181], v[36:37], off
	global_load_dwordx4 v[182:185], v[36:37], off offset:256
	v_lshl_add_u64 v[36:37], v[36:37], 0, s[4:5]
	global_load_dwordx4 v[186:189], v[36:37], off
	global_load_dwordx4 v[190:193], v[36:37], off offset:256
	v_lshl_add_u64 v[36:37], v[36:37], 0, s[4:5]
	global_load_dwordx4 v[194:197], v[36:37], off
	global_load_dwordx4 v[198:201], v[36:37], off offset:256
	s_mov_b32 s4, 0x1e0000
	v_lshl_add_u64 v[36:37], v[36:37], 0, s[4:5]
	s_mov_b32 s4, 0x60000
	global_load_dwordx4 v[202:205], v[36:37], off
	global_load_dwordx4 v[206:209], v[36:37], off offset:256
	v_lshl_add_u64 v[36:37], v[36:37], 0, s[4:5]
	global_load_dwordx4 v[210:213], v[36:37], off
	global_load_dwordx4 v[214:217], v[36:37], off offset:256
	v_lshl_add_u64 v[36:37], v[36:37], 0, s[4:5]
	global_load_dwordx4 v[218:221], v[36:37], off
	global_load_dwordx4 v[222:225], v[36:37], off offset:256
	v_lshl_add_u64 v[36:37], v[36:37], 0, s[4:5]
	global_load_dwordx4 v[226:229], v[36:37], off
	global_load_dwordx4 v[230:233], v[36:37], off offset:256
	s_mov_b32 s4, 0x10000
	s_waitcnt vmcnt(15)
	v_lshlrev_b32_e32 v248, 16, v134
	v_and_b32_e32 v249, 0xffff0000, v134
	v_lshlrev_b32_e32 v250, 16, v135
	v_and_b32_e32 v251, 0xffff0000, v135
	v_max_f32_e32 v248, 0x1e3ce508, v248
	v_max_f32_e32 v249, 0x1e3ce508, v249
	v_max_f32_e32 v250, 0x1e3ce508, v250
	v_max_f32_e32 v251, 0x1e3ce508, v251
	v_pk_mul_f32 v[130:131], v[130:131], v[248:249]
	v_pk_mul_f32 v[132:133], v[132:133], v[250:251]
	v_lshlrev_b32_e32 v248, 16, v136
	v_and_b32_e32 v249, 0xffff0000, v136
	v_lshlrev_b32_e32 v250, 16, v137
	v_and_b32_e32 v251, 0xffff0000, v137
	v_max_f32_e32 v248, 0x1e3ce508, v248
	v_max_f32_e32 v249, 0x1e3ce508, v249
	v_max_f32_e32 v250, 0x1e3ce508, v250
	v_max_f32_e32 v251, 0x1e3ce508, v251
	v_pk_mul_f32 v[126:127], v[126:127], v[248:249]
	v_pk_mul_f32 v[128:129], v[128:129], v[250:251]
	v_cvt_pk_bf16_f32 v134, v130, v131
	v_cvt_pk_bf16_f32 v135, v132, v133
	v_cvt_pk_bf16_f32 v136, v126, v127
	v_cvt_pk_bf16_f32 v137, v128, v129
	global_store_dwordx4 v[162:163], v[134:137], off
	s_waitcnt vmcnt(15)
	v_lshlrev_b32_e32 v248, 16, v138
	v_and_b32_e32 v249, 0xffff0000, v138
	v_lshlrev_b32_e32 v250, 16, v139
	v_and_b32_e32 v251, 0xffff0000, v139
	v_max_f32_e32 v248, 0x1e3ce508, v248
	v_max_f32_e32 v249, 0x1e3ce508, v249
	v_max_f32_e32 v250, 0x1e3ce508, v250
	v_max_f32_e32 v251, 0x1e3ce508, v251
	v_pk_mul_f32 v[122:123], v[122:123], v[248:249]
	v_pk_mul_f32 v[124:125], v[124:125], v[250:251]
	v_lshlrev_b32_e32 v248, 16, v140
	v_and_b32_e32 v249, 0xffff0000, v140
	v_lshlrev_b32_e32 v250, 16, v141
	v_and_b32_e32 v251, 0xffff0000, v141
	v_max_f32_e32 v248, 0x1e3ce508, v248
	v_max_f32_e32 v249, 0x1e3ce508, v249
	v_max_f32_e32 v250, 0x1e3ce508, v250
	v_max_f32_e32 v251, 0x1e3ce508, v251
	v_pk_mul_f32 v[118:119], v[118:119], v[248:249]
	v_pk_mul_f32 v[120:121], v[120:121], v[250:251]
	v_cvt_pk_bf16_f32 v138, v122, v123
	v_cvt_pk_bf16_f32 v139, v124, v125
	v_cvt_pk_bf16_f32 v140, v118, v119
	v_cvt_pk_bf16_f32 v141, v120, v121
	global_store_dwordx4 v[162:163], v[138:141], off offset:256
	v_lshl_add_u64 v[162:163], v[162:163], 0, s[4:5]
	s_waitcnt vmcnt(15)
	v_lshlrev_b32_e32 v248, 16, v178
	v_and_b32_e32 v249, 0xffff0000, v178
	v_lshlrev_b32_e32 v250, 16, v179
	v_and_b32_e32 v251, 0xffff0000, v179
	v_max_f32_e32 v248, 0x1e3ce508, v248
	v_max_f32_e32 v249, 0x1e3ce508, v249
	v_max_f32_e32 v250, 0x1e3ce508, v250
	v_max_f32_e32 v251, 0x1e3ce508, v251
	v_pk_mul_f32 v[114:115], v[114:115], v[248:249]
	v_pk_mul_f32 v[116:117], v[116:117], v[250:251]
	v_lshlrev_b32_e32 v248, 16, v180
	v_and_b32_e32 v249, 0xffff0000, v180
	v_lshlrev_b32_e32 v250, 16, v181
	v_and_b32_e32 v251, 0xffff0000, v181
	v_max_f32_e32 v248, 0x1e3ce508, v248
	v_max_f32_e32 v249, 0x1e3ce508, v249
	v_max_f32_e32 v250, 0x1e3ce508, v250
	v_max_f32_e32 v251, 0x1e3ce508, v251
	v_pk_mul_f32 v[110:111], v[110:111], v[248:249]
	v_pk_mul_f32 v[112:113], v[112:113], v[250:251]
	v_cvt_pk_bf16_f32 v178, v114, v115
	v_cvt_pk_bf16_f32 v179, v116, v117
	v_cvt_pk_bf16_f32 v180, v110, v111
	v_cvt_pk_bf16_f32 v181, v112, v113
	global_store_dwordx4 v[162:163], v[178:181], off
	s_waitcnt vmcnt(15)
	v_lshlrev_b32_e32 v248, 16, v182
	v_and_b32_e32 v249, 0xffff0000, v182
	v_lshlrev_b32_e32 v250, 16, v183
	v_and_b32_e32 v251, 0xffff0000, v183
	v_max_f32_e32 v248, 0x1e3ce508, v248
	v_max_f32_e32 v249, 0x1e3ce508, v249
	v_max_f32_e32 v250, 0x1e3ce508, v250
	v_max_f32_e32 v251, 0x1e3ce508, v251
	v_pk_mul_f32 v[106:107], v[106:107], v[248:249]
	v_pk_mul_f32 v[108:109], v[108:109], v[250:251]
	v_lshlrev_b32_e32 v248, 16, v184
	v_and_b32_e32 v249, 0xffff0000, v184
	v_lshlrev_b32_e32 v250, 16, v185
	v_and_b32_e32 v251, 0xffff0000, v185
	v_max_f32_e32 v248, 0x1e3ce508, v248
	v_max_f32_e32 v249, 0x1e3ce508, v249
	v_max_f32_e32 v250, 0x1e3ce508, v250
	v_max_f32_e32 v251, 0x1e3ce508, v251
	v_pk_mul_f32 v[102:103], v[102:103], v[248:249]
	v_pk_mul_f32 v[104:105], v[104:105], v[250:251]
	v_cvt_pk_bf16_f32 v182, v106, v107
	v_cvt_pk_bf16_f32 v183, v108, v109
	v_cvt_pk_bf16_f32 v184, v102, v103
	v_cvt_pk_bf16_f32 v185, v104, v105
	global_store_dwordx4 v[162:163], v[182:185], off offset:256
	v_lshl_add_u64 v[162:163], v[162:163], 0, s[4:5]
	s_waitcnt vmcnt(15)
; __device__ __forceinline__ unsigned pk2(float lo, float hi) { f32x2 v = {lo, hi}; bf16x2_t b = __builtin_convertvector(v, bf16x2_t); return __builtin_bit_cast(unsigned, b); }
;     __device__ __forceinline__ void operator()(const f32x4 (&acc)[2][2][4][2], const Unit& u, int wr, int wc, int fr, int fq) const {
;     ...
;                 const size_t row = (size_t)(row0 + ai * 128 + m * 16);
; #pragma unroll
;                 for (int bj = 0; bj < 2; ++bj) {
;                     const int col = col0 + bj * 128;
;                     const u32x4 g = *(const u32x4*)(P + row * PS + C_GATE + 4096 + col);
;                     f32x4 v0 = acc[ai][bj][m][0], v1 = acc[ai][bj][m][1];
;                     v0[0] *= fmaxf(bflo(g.x), 1e-20f); v0[1] *= fmaxf(bfhi(g.x), 1e-20f); v0[2] *= fmaxf(bflo(g.y), 1e-20f); v0[3] *= fmaxf(bfhi(g.y), 1e-20f);
;                     v1[0] *= fmaxf(bflo(g.z), 1e-20f); v1[1] *= fmaxf(bfhi(g.z), 1e-20f); v1[2] *= fmaxf(bflo(g.w), 1e-20f); v1[3] *= fmaxf(bfhi(g.w), 1e-20f);
;                     u32x4 w; w.x = pk2(v0[0], v0[1]); w.y = pk2(v0[2], v0[3]); w.z = pk2(v1[0], v1[1]); w.w = pk2(v1[2], v1[3]);
;                     *(u32x4*)(Yb + row * DM + col) = w;
	v_lshlrev_b32_e32 v248, 16, v186
	v_and_b32_e32 v249, 0xffff0000, v186
	v_lshlrev_b32_e32 v250, 16, v187
	v_and_b32_e32 v251, 0xffff0000, v187
	v_max_f32_e32 v248, 0x1e3ce508, v248
	v_max_f32_e32 v249, 0x1e3ce508, v249
	v_max_f32_e32 v250, 0x1e3ce508, v250
	v_max_f32_e32 v251, 0x1e3ce508, v251
	v_pk_mul_f32 v[98:99], v[98:99], v[248:249]
	v_pk_mul_f32 v[100:101], v[100:101], v[250:251]
	v_lshlrev_b32_e32 v248, 16, v188
	v_and_b32_e32 v249, 0xffff0000, v188
	v_lshlrev_b32_e32 v250, 16, v189
	v_and_b32_e32 v251, 0xffff0000, v189
	v_max_f32_e32 v248, 0x1e3ce508, v248
	v_max_f32_e32 v249, 0x1e3ce508, v249
	v_max_f32_e32 v250, 0x1e3ce508, v250
	v_max_f32_e32 v251, 0x1e3ce508, v251
	v_pk_mul_f32 v[94:95], v[94:95], v[248:249]
	v_pk_mul_f32 v[96:97], v[96:97], v[250:251]
	v_cvt_pk_bf16_f32 v186, v98, v99
	v_cvt_pk_bf16_f32 v187, v100, v101
	v_cvt_pk_bf16_f32 v188, v94, v95
	v_cvt_pk_bf16_f32 v189, v96, v97
	global_store_dwordx4 v[162:163], v[186:189], off
	s_waitcnt vmcnt(15)
	v_lshlrev_b32_e32 v248, 16, v190
	v_and_b32_e32 v249, 0xffff0000, v190
	v_lshlrev_b32_e32 v250, 16, v191
	v_and_b32_e32 v251, 0xffff0000, v191
	v_max_f32_e32 v248, 0x1e3ce508, v248
	v_max_f32_e32 v249, 0x1e3ce508, v249
	v_max_f32_e32 v250, 0x1e3ce508, v250
	v_max_f32_e32 v251, 0x1e3ce508, v251
	v_pk_mul_f32 v[90:91], v[90:91], v[248:249]
	v_pk_mul_f32 v[92:93], v[92:93], v[250:251]
	v_lshlrev_b32_e32 v248, 16, v192
	v_and_b32_e32 v249, 0xffff0000, v192
	v_lshlrev_b32_e32 v250, 16, v193
	v_and_b32_e32 v251, 0xffff0000, v193
	v_max_f32_e32 v248, 0x1e3ce508, v248
	v_max_f32_e32 v249, 0x1e3ce508, v249
	v_max_f32_e32 v250, 0x1e3ce508, v250
	v_max_f32_e32 v251, 0x1e3ce508, v251
	v_pk_mul_f32 v[86:87], v[86:87], v[248:249]
	v_pk_mul_f32 v[88:89], v[88:89], v[250:251]
	v_cvt_pk_bf16_f32 v190, v90, v91
	v_cvt_pk_bf16_f32 v191, v92, v93
	v_cvt_pk_bf16_f32 v192, v86, v87
	v_cvt_pk_bf16_f32 v193, v88, v89
	global_store_dwordx4 v[162:163], v[190:193], off offset:256
	v_lshl_add_u64 v[162:163], v[162:163], 0, s[4:5]
	s_waitcnt vmcnt(15)
	v_lshlrev_b32_e32 v248, 16, v194
	v_and_b32_e32 v249, 0xffff0000, v194
	v_lshlrev_b32_e32 v250, 16, v195
	v_and_b32_e32 v251, 0xffff0000, v195
	v_max_f32_e32 v248, 0x1e3ce508, v248
	v_max_f32_e32 v249, 0x1e3ce508, v249
	v_max_f32_e32 v250, 0x1e3ce508, v250
	v_max_f32_e32 v251, 0x1e3ce508, v251
	v_pk_mul_f32 v[82:83], v[82:83], v[248:249]
	v_pk_mul_f32 v[84:85], v[84:85], v[250:251]
	v_lshlrev_b32_e32 v248, 16, v196
	v_and_b32_e32 v249, 0xffff0000, v196
	v_lshlrev_b32_e32 v250, 16, v197
	v_and_b32_e32 v251, 0xffff0000, v197
	v_max_f32_e32 v248, 0x1e3ce508, v248
	v_max_f32_e32 v249, 0x1e3ce508, v249
	v_max_f32_e32 v250, 0x1e3ce508, v250
	v_max_f32_e32 v251, 0x1e3ce508, v251
	v_pk_mul_f32 v[78:79], v[78:79], v[248:249]
	v_pk_mul_f32 v[80:81], v[80:81], v[250:251]
	v_cvt_pk_bf16_f32 v194, v82, v83
	v_cvt_pk_bf16_f32 v195, v84, v85
	v_cvt_pk_bf16_f32 v196, v78, v79
	v_cvt_pk_bf16_f32 v197, v80, v81
	global_store_dwordx4 v[162:163], v[194:197], off
	s_waitcnt vmcnt(15)
	v_lshlrev_b32_e32 v248, 16, v198
	v_and_b32_e32 v249, 0xffff0000, v198
	v_lshlrev_b32_e32 v250, 16, v199
	v_and_b32_e32 v251, 0xffff0000, v199
	v_max_f32_e32 v248, 0x1e3ce508, v248
	v_max_f32_e32 v249, 0x1e3ce508, v249
	v_max_f32_e32 v250, 0x1e3ce508, v250
	v_max_f32_e32 v251, 0x1e3ce508, v251
	v_pk_mul_f32 v[74:75], v[74:75], v[248:249]
	v_pk_mul_f32 v[76:77], v[76:77], v[250:251]
	v_lshlrev_b32_e32 v248, 16, v200
	v_and_b32_e32 v249, 0xffff0000, v200
	v_lshlrev_b32_e32 v250, 16, v201
	v_and_b32_e32 v251, 0xffff0000, v201
	v_max_f32_e32 v248, 0x1e3ce508, v248
	v_max_f32_e32 v249, 0x1e3ce508, v249
	v_max_f32_e32 v250, 0x1e3ce508, v250
	v_max_f32_e32 v251, 0x1e3ce508, v251
	v_pk_mul_f32 v[70:71], v[70:71], v[248:249]
	v_pk_mul_f32 v[72:73], v[72:73], v[250:251]
	v_cvt_pk_bf16_f32 v198, v74, v75
	v_cvt_pk_bf16_f32 v199, v76, v77
	v_cvt_pk_bf16_f32 v200, v70, v71
	v_cvt_pk_bf16_f32 v201, v72, v73
	global_store_dwordx4 v[162:163], v[198:201], off offset:256
	s_mov_b32 s4, 0x50000
	v_lshl_add_u64 v[162:163], v[162:163], 0, s[4:5]
	s_mov_b32 s4, 0x10000
	s_waitcnt vmcnt(15)
	v_lshlrev_b32_e32 v248, 16, v202
	v_and_b32_e32 v249, 0xffff0000, v202
	v_lshlrev_b32_e32 v250, 16, v203
	v_and_b32_e32 v251, 0xffff0000, v203
	v_max_f32_e32 v248, 0x1e3ce508, v248
	v_max_f32_e32 v249, 0x1e3ce508, v249
	v_max_f32_e32 v250, 0x1e3ce508, v250
	v_max_f32_e32 v251, 0x1e3ce508, v251
	v_pk_mul_f32 v[66:67], v[66:67], v[248:249]
	v_pk_mul_f32 v[68:69], v[68:69], v[250:251]
	v_lshlrev_b32_e32 v248, 16, v204
	v_and_b32_e32 v249, 0xffff0000, v204
	v_lshlrev_b32_e32 v250, 16, v205
	v_and_b32_e32 v251, 0xffff0000, v205
	v_max_f32_e32 v248, 0x1e3ce508, v248
	v_max_f32_e32 v249, 0x1e3ce508, v249
	v_max_f32_e32 v250, 0x1e3ce508, v250
	v_max_f32_e32 v251, 0x1e3ce508, v251
	v_pk_mul_f32 v[62:63], v[62:63], v[248:249]
	v_pk_mul_f32 v[64:65], v[64:65], v[250:251]
	v_cvt_pk_bf16_f32 v202, v66, v67
	v_cvt_pk_bf16_f32 v203, v68, v69
	v_cvt_pk_bf16_f32 v204, v62, v63
	v_cvt_pk_bf16_f32 v205, v64, v65
	global_store_dwordx4 v[162:163], v[202:205], off
	s_waitcnt vmcnt(15)
	v_lshlrev_b32_e32 v248, 16, v206
	v_and_b32_e32 v249, 0xffff0000, v206
	v_lshlrev_b32_e32 v250, 16, v207
	v_and_b32_e32 v251, 0xffff0000, v207
	v_max_f32_e32 v248, 0x1e3ce508, v248
	v_max_f32_e32 v249, 0x1e3ce508, v249
	v_max_f32_e32 v250, 0x1e3ce508, v250
	v_max_f32_e32 v251, 0x1e3ce508, v251
	v_pk_mul_f32 v[58:59], v[58:59], v[248:249]
	v_pk_mul_f32 v[60:61], v[60:61], v[250:251]
	v_lshlrev_b32_e32 v248, 16, v208
	v_and_b32_e32 v249, 0xffff0000, v208
	v_lshlrev_b32_e32 v250, 16, v209
	v_and_b32_e32 v251, 0xffff0000, v209
	v_max_f32_e32 v248, 0x1e3ce508, v248
	v_max_f32_e32 v249, 0x1e3ce508, v249
	v_max_f32_e32 v250, 0x1e3ce508, v250
	v_max_f32_e32 v251, 0x1e3ce508, v251
	v_pk_mul_f32 v[54:55], v[54:55], v[248:249]
	v_pk_mul_f32 v[56:57], v[56:57], v[250:251]
	v_cvt_pk_bf16_f32 v206, v58, v59
	v_cvt_pk_bf16_f32 v207, v60, v61
	v_cvt_pk_bf16_f32 v208, v54, v55
	v_cvt_pk_bf16_f32 v209, v56, v57
	global_store_dwordx4 v[162:163], v[206:209], off offset:256
	v_lshl_add_u64 v[162:163], v[162:163], 0, s[4:5]
	s_waitcnt vmcnt(15)
; #define PG8_BAR __builtin_amdgcn_s_barrier()
; __device__ __forceinline__ unsigned pk2(float lo, float hi) { f32x2 v = {lo, hi}; bf16x2_t b = __builtin_convertvector(v, bf16x2_t); return __builtin_bit_cast(unsigned, b); }
; template <class Epi, class Sched, bool ALIGN_EPI = false, bool SP2 = false>
; __device__ __forceinline__ void gemm_phase(PG8_LAS unsigned char* lds, const Gemm g, const Sched& S, const Epi& E) {
;     ...
;         if (!has_next) break;
; #pragma unroll
;         for (int a = 0; a < 2; ++a)
; #pragma unroll
;             for (int b = 0; b < 2; ++b)
; #pragma unroll
;                 for (int m = 0; m < 4; ++m)
; #pragma unroll
;                     for (int n = 0; n < 2; ++n) acc[a][b][m][n] = (f32x4){0.f, 0.f, 0.f, 0.f};
;         cur = nxt; cA = nA; cB = nB; ++ui;
;         if constexpr (ALIGN_EPI) { if (wr == 1) PG8_BAR; }
;     __device__ __forceinline__ void operator()(const f32x4 (&acc)[2][2][4][2], const Unit& u, int wr, int wc, int fr, int fq) const {
;     ...
;                 const size_t row = (size_t)(row0 + ai * 128 + m * 16);
; #pragma unroll
;                 for (int bj = 0; bj < 2; ++bj) {
;                     const int col = col0 + bj * 128;
;                     const u32x4 g = *(const u32x4*)(P + row * PS + C_GATE + 4096 + col);
;                     f32x4 v0 = acc[ai][bj][m][0], v1 = acc[ai][bj][m][1];
;                     v0[0] *= fmaxf(bflo(g.x), 1e-20f); v0[1] *= fmaxf(bfhi(g.x), 1e-20f); v0[2] *= fmaxf(bflo(g.y), 1e-20f); v0[3] *= fmaxf(bfhi(g.y), 1e-20f);
;                     v1[0] *= fmaxf(bflo(g.z), 1e-20f); v1[1] *= fmaxf(bfhi(g.z), 1e-20f); v1[2] *= fmaxf(bflo(g.w), 1e-20f); v1[3] *= fmaxf(bfhi(g.w), 1e-20f);
;                     u32x4 w; w.x = pk2(v0[0], v0[1]); w.y = pk2(v0[2], v0[3]); w.z = pk2(v1[0], v1[1]); w.w = pk2(v1[2], v1[3]);
;                     *(u32x4*)(Yb + row * DM + col) = w;
	v_lshlrev_b32_e32 v248, 16, v210
	v_and_b32_e32 v249, 0xffff0000, v210
	v_lshlrev_b32_e32 v250, 16, v211
	v_and_b32_e32 v251, 0xffff0000, v211
	v_max_f32_e32 v248, 0x1e3ce508, v248
	v_max_f32_e32 v249, 0x1e3ce508, v249
	v_max_f32_e32 v250, 0x1e3ce508, v250
	v_max_f32_e32 v251, 0x1e3ce508, v251
	v_pk_mul_f32 v[50:51], v[50:51], v[248:249]
	v_pk_mul_f32 v[52:53], v[52:53], v[250:251]
	v_lshlrev_b32_e32 v248, 16, v212
	v_and_b32_e32 v249, 0xffff0000, v212
	v_lshlrev_b32_e32 v250, 16, v213
	v_and_b32_e32 v251, 0xffff0000, v213
	v_max_f32_e32 v248, 0x1e3ce508, v248
	v_max_f32_e32 v249, 0x1e3ce508, v249
	v_max_f32_e32 v250, 0x1e3ce508, v250
	v_max_f32_e32 v251, 0x1e3ce508, v251
	v_pk_mul_f32 v[46:47], v[46:47], v[248:249]
	v_pk_mul_f32 v[48:49], v[48:49], v[250:251]
	v_cvt_pk_bf16_f32 v210, v50, v51
	v_cvt_pk_bf16_f32 v211, v52, v53
	v_cvt_pk_bf16_f32 v212, v46, v47
	v_cvt_pk_bf16_f32 v213, v48, v49
	global_store_dwordx4 v[162:163], v[210:213], off
	s_waitcnt vmcnt(15)
	v_lshlrev_b32_e32 v248, 16, v214
	v_and_b32_e32 v249, 0xffff0000, v214
	v_lshlrev_b32_e32 v250, 16, v215
	v_and_b32_e32 v251, 0xffff0000, v215
	v_max_f32_e32 v248, 0x1e3ce508, v248
	v_max_f32_e32 v249, 0x1e3ce508, v249
	v_max_f32_e32 v250, 0x1e3ce508, v250
	v_max_f32_e32 v251, 0x1e3ce508, v251
	v_pk_mul_f32 v[42:43], v[42:43], v[248:249]
	v_pk_mul_f32 v[44:45], v[44:45], v[250:251]
	v_lshlrev_b32_e32 v248, 16, v216
	v_and_b32_e32 v249, 0xffff0000, v216
	v_lshlrev_b32_e32 v250, 16, v217
	v_and_b32_e32 v251, 0xffff0000, v217
	v_max_f32_e32 v248, 0x1e3ce508, v248
	v_max_f32_e32 v249, 0x1e3ce508, v249
	v_max_f32_e32 v250, 0x1e3ce508, v250
	v_max_f32_e32 v251, 0x1e3ce508, v251
	v_pk_mul_f32 v[38:39], v[38:39], v[248:249]
	v_pk_mul_f32 v[40:41], v[40:41], v[250:251]
	v_cvt_pk_bf16_f32 v214, v42, v43
	v_cvt_pk_bf16_f32 v215, v44, v45
	v_cvt_pk_bf16_f32 v216, v38, v39
	v_cvt_pk_bf16_f32 v217, v40, v41
	global_store_dwordx4 v[162:163], v[214:217], off offset:256
	v_lshl_add_u64 v[162:163], v[162:163], 0, s[4:5]
	s_waitcnt vmcnt(15)
	v_lshlrev_b32_e32 v248, 16, v218
	v_and_b32_e32 v249, 0xffff0000, v218
	v_lshlrev_b32_e32 v250, 16, v219
	v_and_b32_e32 v251, 0xffff0000, v219
	v_max_f32_e32 v248, 0x1e3ce508, v248
	v_max_f32_e32 v249, 0x1e3ce508, v249
	v_max_f32_e32 v250, 0x1e3ce508, v250
	v_max_f32_e32 v251, 0x1e3ce508, v251
	v_pk_mul_f32 v[28:29], v[28:29], v[248:249]
	v_pk_mul_f32 v[30:31], v[30:31], v[250:251]
	v_lshlrev_b32_e32 v248, 16, v220
	v_and_b32_e32 v249, 0xffff0000, v220
	v_lshlrev_b32_e32 v250, 16, v221
	v_and_b32_e32 v251, 0xffff0000, v221
	v_max_f32_e32 v248, 0x1e3ce508, v248
	v_max_f32_e32 v249, 0x1e3ce508, v249
	v_max_f32_e32 v250, 0x1e3ce508, v250
	v_max_f32_e32 v251, 0x1e3ce508, v251
	v_pk_mul_f32 v[24:25], v[24:25], v[248:249]
	v_pk_mul_f32 v[26:27], v[26:27], v[250:251]
	v_cvt_pk_bf16_f32 v218, v28, v29
	v_cvt_pk_bf16_f32 v219, v30, v31
	v_cvt_pk_bf16_f32 v220, v24, v25
	v_cvt_pk_bf16_f32 v221, v26, v27
	global_store_dwordx4 v[162:163], v[218:221], off
	s_waitcnt vmcnt(15)
	v_lshlrev_b32_e32 v248, 16, v222
	v_and_b32_e32 v249, 0xffff0000, v222
	v_lshlrev_b32_e32 v250, 16, v223
	v_and_b32_e32 v251, 0xffff0000, v223
	v_max_f32_e32 v248, 0x1e3ce508, v248
	v_max_f32_e32 v249, 0x1e3ce508, v249
	v_max_f32_e32 v250, 0x1e3ce508, v250
	v_max_f32_e32 v251, 0x1e3ce508, v251
	v_pk_mul_f32 v[20:21], v[20:21], v[248:249]
	v_pk_mul_f32 v[22:23], v[22:23], v[250:251]
	v_lshlrev_b32_e32 v248, 16, v224
	v_and_b32_e32 v249, 0xffff0000, v224
	v_lshlrev_b32_e32 v250, 16, v225
	v_and_b32_e32 v251, 0xffff0000, v225
	v_max_f32_e32 v248, 0x1e3ce508, v248
	v_max_f32_e32 v249, 0x1e3ce508, v249
	v_max_f32_e32 v250, 0x1e3ce508, v250
	v_max_f32_e32 v251, 0x1e3ce508, v251
	v_pk_mul_f32 v[16:17], v[16:17], v[248:249]
	v_pk_mul_f32 v[18:19], v[18:19], v[250:251]
	v_cvt_pk_bf16_f32 v222, v20, v21
	v_cvt_pk_bf16_f32 v223, v22, v23
	v_cvt_pk_bf16_f32 v224, v16, v17
	v_cvt_pk_bf16_f32 v225, v18, v19
	global_store_dwordx4 v[162:163], v[222:225], off offset:256
	v_lshl_add_u64 v[162:163], v[162:163], 0, s[4:5]
	s_waitcnt vmcnt(15)
	v_lshlrev_b32_e32 v248, 16, v226
	v_and_b32_e32 v249, 0xffff0000, v226
	v_lshlrev_b32_e32 v250, 16, v227
	v_and_b32_e32 v251, 0xffff0000, v227
	v_max_f32_e32 v248, 0x1e3ce508, v248
	v_max_f32_e32 v249, 0x1e3ce508, v249
	v_max_f32_e32 v250, 0x1e3ce508, v250
	v_max_f32_e32 v251, 0x1e3ce508, v251
	v_pk_mul_f32 v[12:13], v[12:13], v[248:249]
	v_pk_mul_f32 v[14:15], v[14:15], v[250:251]
	v_lshlrev_b32_e32 v248, 16, v228
	v_and_b32_e32 v249, 0xffff0000, v228
	v_lshlrev_b32_e32 v250, 16, v229
	v_and_b32_e32 v251, 0xffff0000, v229
	v_max_f32_e32 v248, 0x1e3ce508, v248
	v_max_f32_e32 v249, 0x1e3ce508, v249
	v_max_f32_e32 v250, 0x1e3ce508, v250
	v_max_f32_e32 v251, 0x1e3ce508, v251
	v_pk_mul_f32 v[8:9], v[8:9], v[248:249]
	v_pk_mul_f32 v[10:11], v[10:11], v[250:251]
	v_cvt_pk_bf16_f32 v226, v12, v13
	v_cvt_pk_bf16_f32 v227, v14, v15
	v_cvt_pk_bf16_f32 v228, v8, v9
	v_cvt_pk_bf16_f32 v229, v10, v11
	global_store_dwordx4 v[162:163], v[226:229], off
	s_waitcnt vmcnt(15)
	v_lshlrev_b32_e32 v248, 16, v230
	v_and_b32_e32 v249, 0xffff0000, v230
	v_lshlrev_b32_e32 v250, 16, v231
	v_and_b32_e32 v251, 0xffff0000, v231
	v_max_f32_e32 v248, 0x1e3ce508, v248
	v_max_f32_e32 v249, 0x1e3ce508, v249
	v_max_f32_e32 v250, 0x1e3ce508, v250
	v_max_f32_e32 v251, 0x1e3ce508, v251
	v_pk_mul_f32 v[4:5], v[4:5], v[248:249]
	v_pk_mul_f32 v[6:7], v[6:7], v[250:251]
	v_lshlrev_b32_e32 v248, 16, v232
	v_and_b32_e32 v249, 0xffff0000, v232
	v_lshlrev_b32_e32 v250, 16, v233
	v_and_b32_e32 v251, 0xffff0000, v233
	v_max_f32_e32 v248, 0x1e3ce508, v248
	v_max_f32_e32 v249, 0x1e3ce508, v249
	v_max_f32_e32 v250, 0x1e3ce508, v250
	v_max_f32_e32 v251, 0x1e3ce508, v251
	v_pk_mul_f32 v[0:1], v[0:1], v[248:249]
	v_pk_mul_f32 v[2:3], v[2:3], v[250:251]
	v_cvt_pk_bf16_f32 v230, v4, v5
	v_cvt_pk_bf16_f32 v231, v6, v7
	v_cvt_pk_bf16_f32 v232, v0, v1
	v_cvt_pk_bf16_f32 v233, v2, v3
	global_store_dwordx4 v[162:163], v[230:233], off offset:256
	s_andn2_b64 vcc, exec, s[56:57]
	s_mov_b64 s[0:1], -1
	s_cbranch_vccnz .LBB0_742
	s_andn2_b64 vcc, exec, s[38:39]
	s_cbranch_vccnz .LBB0_741
	s_barrier
	s_branch .LBB0_741

; __device__ __forceinline__ float fast_rcp(float x) { return __builtin_amdgcn_rcpf(x); }
;     __device__ __forceinline__ void mid(f32x4 (&acc)[2][2][4][2], const Unit& u, int wr, int wc, int fr, int fq, int t) const {
;     ...
;                 const bf16_t* gp = P + (size_t)(row0 + ai * 128 + m * 16) * PS + noff + col0;
; #pragma unroll
;                 for (int bj = 0; bj < 2; ++bj) {
;                     const u32x4 gn = *(const u32x4*)(gp + bj * 128), gd = *(const u32x4*)(gp + bj * 128 + 2048);
;                     f32x4 r0, r1;
;                     r0[0] = bflo(gn.x) * fast_rcp(fmaxf(bflo(gd.x), 1e-20f)); r0[1] = bfhi(gn.x) * fast_rcp(fmaxf(bfhi(gd.x), 1e-20f));
;                     r0[2] = bflo(gn.y) * fast_rcp(fmaxf(bflo(gd.y), 1e-20f)); r0[3] = bfhi(gn.y) * fast_rcp(fmaxf(bfhi(gd.y), 1e-20f));
;                     r1[0] = bflo(gn.z) * fast_rcp(fmaxf(bflo(gd.z), 1e-20f)); r1[1] = bfhi(gn.z) * fast_rcp(fmaxf(bfhi(gd.z), 1e-20f));
;                     r1[2] = bflo(gn.w) * fast_rcp(fmaxf(bflo(gd.w), 1e-20f)); r1[3] = bfhi(gn.w) * fast_rcp(fmaxf(bfhi(gd.w), 1e-20f));
;                     acc[ai][bj][m][0] *= r0; acc[ai][bj][m][1] *= r1;
.LBB0_788:
	s_andn2_b64 vcc, exec, s[6:7]
	s_cbranch_vccnz .LBB0_790
	v_add_u32_e32 v34, s68, v173
	s_cmp_eq_u32 s12, 8
	v_mov_b64_e32 v[36:37], s[40:41]
	s_cselect_b32 s24, s20, 0x4000
	v_mad_i64_i32 v[36:37], vcc, v34, s90, v[36:37]
	s_mov_b32 s5, 0
	v_lshl_add_u64 v[36:37], v[36:37], 0, s[24:25]
	s_movk_i32 s4, 0x800
	v_lshl_add_u64 v[36:37], v[36:37], 0, v[164:165]
	v_lshl_add_u64 v[36:37], v[36:37], 0, s[4:5]
	s_mov_b32 s4, 0x60000
	global_load_dwordx4 v[134:137], v[36:37], off offset:-2048
	global_load_dwordx4 v[138:141], v[36:37], off offset:2048
	global_load_dwordx4 v[178:181], v[36:37], off offset:-1792
	global_load_dwordx4 v[182:185], v[36:37], off offset:2304
	v_lshl_add_u64 v[36:37], v[36:37], 0, s[4:5]
	global_load_dwordx4 v[186:189], v[36:37], off offset:-2048
	global_load_dwordx4 v[190:193], v[36:37], off offset:2048
	global_load_dwordx4 v[194:197], v[36:37], off offset:-1792
	global_load_dwordx4 v[198:201], v[36:37], off offset:2304
	v_lshl_add_u64 v[36:37], v[36:37], 0, s[4:5]
	global_load_dwordx4 v[202:205], v[36:37], off offset:-2048
	global_load_dwordx4 v[206:209], v[36:37], off offset:2048
	global_load_dwordx4 v[210:213], v[36:37], off offset:-1792
	global_load_dwordx4 v[214:217], v[36:37], off offset:2304
	v_lshl_add_u64 v[36:37], v[36:37], 0, s[4:5]
	global_load_dwordx4 v[218:221], v[36:37], off offset:-2048
	global_load_dwordx4 v[222:225], v[36:37], off offset:2048
	global_load_dwordx4 v[226:229], v[36:37], off offset:-1792
	global_load_dwordx4 v[230:233], v[36:37], off offset:2304
	v_lshl_add_u64 v[36:37], v[36:37], 0, s[4:5]
	s_mov_b32 s4, 0x180000
	v_lshl_add_u64 v[36:37], v[36:37], 0, s[4:5]
	s_mov_b32 s4, 0x60000
	s_waitcnt vmcnt(14)
	v_lshlrev_b32_e32 v248, 16, v138
	v_and_b32_e32 v249, 0xffff0000, v138
	v_lshlrev_b32_e32 v250, 16, v139
	v_and_b32_e32 v251, 0xffff0000, v139
	v_max_f32_e32 v248, 0x1e3ce508, v248
	v_max_f32_e32 v249, 0x1e3ce508, v249
	v_max_f32_e32 v250, 0x1e3ce508, v250
	v_max_f32_e32 v251, 0x1e3ce508, v251
	v_rcp_f32_e32 v248, v248
	v_rcp_f32_e32 v249, v249
	v_rcp_f32_e32 v250, v250
	v_rcp_f32_e32 v251, v251
	v_lshlrev_b32_e32 v252, 16, v134
	v_and_b32_e32 v253, 0xffff0000, v134
	v_lshlrev_b32_e32 v254, 16, v135
	v_and_b32_e32 v255, 0xffff0000, v135
	v_pk_mul_f32 v[248:249], v[248:249], v[252:253]
	v_pk_mul_f32 v[250:251], v[250:251], v[254:255]
	v_pk_mul_f32 v[130:131], v[130:131], v[248:249]
	v_pk_mul_f32 v[132:133], v[132:133], v[250:251]
	v_lshlrev_b32_e32 v248, 16, v140
	v_and_b32_e32 v249, 0xffff0000, v140
	v_lshlrev_b32_e32 v250, 16, v141
	v_and_b32_e32 v251, 0xffff0000, v141
	v_max_f32_e32 v248, 0x1e3ce508, v248
	v_max_f32_e32 v249, 0x1e3ce508, v249
	v_max_f32_e32 v250, 0x1e3ce508, v250
	v_max_f32_e32 v251, 0x1e3ce508, v251
	v_rcp_f32_e32 v248, v248
	v_rcp_f32_e32 v249, v249
	v_rcp_f32_e32 v250, v250
	v_rcp_f32_e32 v251, v251
	v_lshlrev_b32_e32 v252, 16, v136
	v_and_b32_e32 v253, 0xffff0000, v136
	v_lshlrev_b32_e32 v254, 16, v137
	v_and_b32_e32 v255, 0xffff0000, v137
	v_pk_mul_f32 v[248:249], v[248:249], v[252:253]
	v_pk_mul_f32 v[250:251], v[250:251], v[254:255]
	v_pk_mul_f32 v[126:127], v[126:127], v[248:249]
	v_pk_mul_f32 v[128:129], v[128:129], v[250:251]
	global_load_dwordx4 v[134:137], v[36:37], off offset:-2048
	global_load_dwordx4 v[138:141], v[36:37], off offset:2048
	s_waitcnt vmcnt(14)
	v_lshlrev_b32_e32 v248, 16, v182
	v_and_b32_e32 v249, 0xffff0000, v182
	v_lshlrev_b32_e32 v250, 16, v183
	v_and_b32_e32 v251, 0xffff0000, v183
	v_max_f32_e32 v248, 0x1e3ce508, v248
	v_max_f32_e32 v249, 0x1e3ce508, v249
	v_max_f32_e32 v250, 0x1e3ce508, v250
	v_max_f32_e32 v251, 0x1e3ce508, v251
	v_rcp_f32_e32 v248, v248
	v_rcp_f32_e32 v249, v249
	v_rcp_f32_e32 v250, v250
	v_rcp_f32_e32 v251, v251
	v_lshlrev_b32_e32 v252, 16, v178
	v_and_b32_e32 v253, 0xffff0000, v178
	v_lshlrev_b32_e32 v254, 16, v179
	v_and_b32_e32 v255, 0xffff0000, v179
	v_pk_mul_f32 v[248:249], v[248:249], v[252:253]
	v_pk_mul_f32 v[250:251], v[250:251], v[254:255]
	v_pk_mul_f32 v[122:123], v[122:123], v[248:249]
	v_pk_mul_f32 v[124:125], v[124:125], v[250:251]
	v_lshlrev_b32_e32 v248, 16, v184
	v_and_b32_e32 v249, 0xffff0000, v184
	v_lshlrev_b32_e32 v250, 16, v185
	v_and_b32_e32 v251, 0xffff0000, v185
	v_max_f32_e32 v248, 0x1e3ce508, v248
	v_max_f32_e32 v249, 0x1e3ce508, v249
	v_max_f32_e32 v250, 0x1e3ce508, v250
	v_max_f32_e32 v251, 0x1e3ce508, v251
	v_rcp_f32_e32 v248, v248
	v_rcp_f32_e32 v249, v249
	v_rcp_f32_e32 v250, v250
	v_rcp_f32_e32 v251, v251
	v_lshlrev_b32_e32 v252, 16, v180
	v_and_b32_e32 v253, 0xffff0000, v180
	v_lshlrev_b32_e32 v254, 16, v181
	v_and_b32_e32 v255, 0xffff0000, v181
	v_pk_mul_f32 v[248:249], v[248:249], v[252:253]
	v_pk_mul_f32 v[250:251], v[250:251], v[254:255]
	v_pk_mul_f32 v[118:119], v[118:119], v[248:249]
	v_pk_mul_f32 v[120:121], v[120:121], v[250:251]
	global_load_dwordx4 v[178:181], v[36:37], off offset:-1792
	global_load_dwordx4 v[182:185], v[36:37], off offset:2304
	v_lshl_add_u64 v[36:37], v[36:37], 0, s[4:5]
	s_waitcnt vmcnt(14)
; __device__ __forceinline__ float fast_rcp(float x) { return __builtin_amdgcn_rcpf(x); }
;     __device__ __forceinline__ void mid(f32x4 (&acc)[2][2][4][2], const Unit& u, int wr, int wc, int fr, int fq, int t) const {
;     ...
;                 const bf16_t* gp = P + (size_t)(row0 + ai * 128 + m * 16) * PS + noff + col0;
; #pragma unroll
;                 for (int bj = 0; bj < 2; ++bj) {
;                     const u32x4 gn = *(const u32x4*)(gp + bj * 128), gd = *(const u32x4*)(gp + bj * 128 + 2048);
;                     f32x4 r0, r1;
;                     r0[0] = bflo(gn.x) * fast_rcp(fmaxf(bflo(gd.x), 1e-20f)); r0[1] = bfhi(gn.x) * fast_rcp(fmaxf(bfhi(gd.x), 1e-20f));
;                     r0[2] = bflo(gn.y) * fast_rcp(fmaxf(bflo(gd.y), 1e-20f)); r0[3] = bfhi(gn.y) * fast_rcp(fmaxf(bfhi(gd.y), 1e-20f));
;                     r1[0] = bflo(gn.z) * fast_rcp(fmaxf(bflo(gd.z), 1e-20f)); r1[1] = bfhi(gn.z) * fast_rcp(fmaxf(bfhi(gd.z), 1e-20f));
;                     r1[2] = bflo(gn.w) * fast_rcp(fmaxf(bflo(gd.w), 1e-20f)); r1[3] = bfhi(gn.w) * fast_rcp(fmaxf(bfhi(gd.w), 1e-20f));
;                     acc[ai][bj][m][0] *= r0; acc[ai][bj][m][1] *= r1;
	v_lshlrev_b32_e32 v248, 16, v190
	v_and_b32_e32 v249, 0xffff0000, v190
	v_lshlrev_b32_e32 v250, 16, v191
	v_and_b32_e32 v251, 0xffff0000, v191
	v_max_f32_e32 v248, 0x1e3ce508, v248
	v_max_f32_e32 v249, 0x1e3ce508, v249
	v_max_f32_e32 v250, 0x1e3ce508, v250
	v_max_f32_e32 v251, 0x1e3ce508, v251
	v_rcp_f32_e32 v248, v248
	v_rcp_f32_e32 v249, v249
	v_rcp_f32_e32 v250, v250
	v_rcp_f32_e32 v251, v251
	v_lshlrev_b32_e32 v252, 16, v186
	v_and_b32_e32 v253, 0xffff0000, v186
	v_lshlrev_b32_e32 v254, 16, v187
	v_and_b32_e32 v255, 0xffff0000, v187
	v_pk_mul_f32 v[248:249], v[248:249], v[252:253]
	v_pk_mul_f32 v[250:251], v[250:251], v[254:255]
	v_pk_mul_f32 v[114:115], v[114:115], v[248:249]
	v_pk_mul_f32 v[116:117], v[116:117], v[250:251]
	v_lshlrev_b32_e32 v248, 16, v192
	v_and_b32_e32 v249, 0xffff0000, v192
	v_lshlrev_b32_e32 v250, 16, v193
	v_and_b32_e32 v251, 0xffff0000, v193
	v_max_f32_e32 v248, 0x1e3ce508, v248
	v_max_f32_e32 v249, 0x1e3ce508, v249
	v_max_f32_e32 v250, 0x1e3ce508, v250
	v_max_f32_e32 v251, 0x1e3ce508, v251
	v_rcp_f32_e32 v248, v248
	v_rcp_f32_e32 v249, v249
	v_rcp_f32_e32 v250, v250
	v_rcp_f32_e32 v251, v251
	v_lshlrev_b32_e32 v252, 16, v188
	v_and_b32_e32 v253, 0xffff0000, v188
	v_lshlrev_b32_e32 v254, 16, v189
	v_and_b32_e32 v255, 0xffff0000, v189
	v_pk_mul_f32 v[248:249], v[248:249], v[252:253]
	v_pk_mul_f32 v[250:251], v[250:251], v[254:255]
	v_pk_mul_f32 v[110:111], v[110:111], v[248:249]
	v_pk_mul_f32 v[112:113], v[112:113], v[250:251]
	global_load_dwordx4 v[186:189], v[36:37], off offset:-2048
	global_load_dwordx4 v[190:193], v[36:37], off offset:2048
	s_waitcnt vmcnt(14)
	v_lshlrev_b32_e32 v248, 16, v198
	v_and_b32_e32 v249, 0xffff0000, v198
	v_lshlrev_b32_e32 v250, 16, v199
	v_and_b32_e32 v251, 0xffff0000, v199
	v_max_f32_e32 v248, 0x1e3ce508, v248
	v_max_f32_e32 v249, 0x1e3ce508, v249
	v_max_f32_e32 v250, 0x1e3ce508, v250
	v_max_f32_e32 v251, 0x1e3ce508, v251
	v_rcp_f32_e32 v248, v248
	v_rcp_f32_e32 v249, v249
	v_rcp_f32_e32 v250, v250
	v_rcp_f32_e32 v251, v251
	v_lshlrev_b32_e32 v252, 16, v194
	v_and_b32_e32 v253, 0xffff0000, v194
	v_lshlrev_b32_e32 v254, 16, v195
	v_and_b32_e32 v255, 0xffff0000, v195
	v_pk_mul_f32 v[248:249], v[248:249], v[252:253]
	v_pk_mul_f32 v[250:251], v[250:251], v[254:255]
	v_pk_mul_f32 v[106:107], v[106:107], v[248:249]
	v_pk_mul_f32 v[108:109], v[108:109], v[250:251]
	v_lshlrev_b32_e32 v248, 16, v200
	v_and_b32_e32 v249, 0xffff0000, v200
	v_lshlrev_b32_e32 v250, 16, v201
	v_and_b32_e32 v251, 0xffff0000, v201
	v_max_f32_e32 v248, 0x1e3ce508, v248
	v_max_f32_e32 v249, 0x1e3ce508, v249
	v_max_f32_e32 v250, 0x1e3ce508, v250
	v_max_f32_e32 v251, 0x1e3ce508, v251
	v_rcp_f32_e32 v248, v248
	v_rcp_f32_e32 v249, v249
	v_rcp_f32_e32 v250, v250
	v_rcp_f32_e32 v251, v251
	v_lshlrev_b32_e32 v252, 16, v196
	v_and_b32_e32 v253, 0xffff0000, v196
	v_lshlrev_b32_e32 v254, 16, v197
	v_and_b32_e32 v255, 0xffff0000, v197
	v_pk_mul_f32 v[248:249], v[248:249], v[252:253]
	v_pk_mul_f32 v[250:251], v[250:251], v[254:255]
	v_pk_mul_f32 v[102:103], v[102:103], v[248:249]
	v_pk_mul_f32 v[104:105], v[104:105], v[250:251]
	global_load_dwordx4 v[194:197], v[36:37], off offset:-1792
	global_load_dwordx4 v[198:201], v[36:37], off offset:2304
	v_lshl_add_u64 v[36:37], v[36:37], 0, s[4:5]
	s_waitcnt vmcnt(14)
	v_lshlrev_b32_e32 v248, 16, v206
	v_and_b32_e32 v249, 0xffff0000, v206
	v_lshlrev_b32_e32 v250, 16, v207
	v_and_b32_e32 v251, 0xffff0000, v207
	v_max_f32_e32 v248, 0x1e3ce508, v248
	v_max_f32_e32 v249, 0x1e3ce508, v249
	v_max_f32_e32 v250, 0x1e3ce508, v250
	v_max_f32_e32 v251, 0x1e3ce508, v251
	v_rcp_f32_e32 v248, v248
	v_rcp_f32_e32 v249, v249
	v_rcp_f32_e32 v250, v250
	v_rcp_f32_e32 v251, v251
	v_lshlrev_b32_e32 v252, 16, v202
	v_and_b32_e32 v253, 0xffff0000, v202
	v_lshlrev_b32_e32 v254, 16, v203
	v_and_b32_e32 v255, 0xffff0000, v203
	v_pk_mul_f32 v[248:249], v[248:249], v[252:253]
	v_pk_mul_f32 v[250:251], v[250:251], v[254:255]
	v_pk_mul_f32 v[98:99], v[98:99], v[248:249]
	v_pk_mul_f32 v[100:101], v[100:101], v[250:251]
	v_lshlrev_b32_e32 v248, 16, v208
	v_and_b32_e32 v249, 0xffff0000, v208
	v_lshlrev_b32_e32 v250, 16, v209
	v_and_b32_e32 v251, 0xffff0000, v209
	v_max_f32_e32 v248, 0x1e3ce508, v248
	v_max_f32_e32 v249, 0x1e3ce508, v249
	v_max_f32_e32 v250, 0x1e3ce508, v250
	v_max_f32_e32 v251, 0x1e3ce508, v251
	v_rcp_f32_e32 v248, v248
	v_rcp_f32_e32 v249, v249
	v_rcp_f32_e32 v250, v250
	v_rcp_f32_e32 v251, v251
	v_lshlrev_b32_e32 v252, 16, v204
	v_and_b32_e32 v253, 0xffff0000, v204
	v_lshlrev_b32_e32 v254, 16, v205
	v_and_b32_e32 v255, 0xffff0000, v205
	v_pk_mul_f32 v[248:249], v[248:249], v[252:253]
	v_pk_mul_f32 v[250:251], v[250:251], v[254:255]
	v_pk_mul_f32 v[94:95], v[94:95], v[248:249]
	v_pk_mul_f32 v[96:97], v[96:97], v[250:251]
	global_load_dwordx4 v[202:205], v[36:37], off offset:-2048
	global_load_dwordx4 v[206:209], v[36:37], off offset:2048
	s_waitcnt vmcnt(14)
; __device__ __forceinline__ float fast_rcp(float x) { return __builtin_amdgcn_rcpf(x); }
;     __device__ __forceinline__ void mid(f32x4 (&acc)[2][2][4][2], const Unit& u, int wr, int wc, int fr, int fq, int t) const {
;     ...
;                 const bf16_t* gp = P + (size_t)(row0 + ai * 128 + m * 16) * PS + noff + col0;
; #pragma unroll
;                 for (int bj = 0; bj < 2; ++bj) {
;                     const u32x4 gn = *(const u32x4*)(gp + bj * 128), gd = *(const u32x4*)(gp + bj * 128 + 2048);
;                     f32x4 r0, r1;
;                     r0[0] = bflo(gn.x) * fast_rcp(fmaxf(bflo(gd.x), 1e-20f)); r0[1] = bfhi(gn.x) * fast_rcp(fmaxf(bfhi(gd.x), 1e-20f));
;                     r0[2] = bflo(gn.y) * fast_rcp(fmaxf(bflo(gd.y), 1e-20f)); r0[3] = bfhi(gn.y) * fast_rcp(fmaxf(bfhi(gd.y), 1e-20f));
;                     r1[0] = bflo(gn.z) * fast_rcp(fmaxf(bflo(gd.z), 1e-20f)); r1[1] = bfhi(gn.z) * fast_rcp(fmaxf(bfhi(gd.z), 1e-20f));
;                     r1[2] = bflo(gn.w) * fast_rcp(fmaxf(bflo(gd.w), 1e-20f)); r1[3] = bfhi(gn.w) * fast_rcp(fmaxf(bfhi(gd.w), 1e-20f));
;                     acc[ai][bj][m][0] *= r0; acc[ai][bj][m][1] *= r1;
;                 }
;                 if (m == 1 || m == 3) __builtin_amdgcn_sched_barrier(0);
	v_lshlrev_b32_e32 v248, 16, v214
	v_and_b32_e32 v249, 0xffff0000, v214
	v_lshlrev_b32_e32 v250, 16, v215
	v_and_b32_e32 v251, 0xffff0000, v215
	v_max_f32_e32 v248, 0x1e3ce508, v248
	v_max_f32_e32 v249, 0x1e3ce508, v249
	v_max_f32_e32 v250, 0x1e3ce508, v250
	v_max_f32_e32 v251, 0x1e3ce508, v251
	v_rcp_f32_e32 v248, v248
	v_rcp_f32_e32 v249, v249
	v_rcp_f32_e32 v250, v250
	v_rcp_f32_e32 v251, v251
	v_lshlrev_b32_e32 v252, 16, v210
	v_and_b32_e32 v253, 0xffff0000, v210
	v_lshlrev_b32_e32 v254, 16, v211
	v_and_b32_e32 v255, 0xffff0000, v211
	v_pk_mul_f32 v[248:249], v[248:249], v[252:253]
	v_pk_mul_f32 v[250:251], v[250:251], v[254:255]
	v_pk_mul_f32 v[90:91], v[90:91], v[248:249]
	v_pk_mul_f32 v[92:93], v[92:93], v[250:251]
	v_lshlrev_b32_e32 v248, 16, v216
	v_and_b32_e32 v249, 0xffff0000, v216
	v_lshlrev_b32_e32 v250, 16, v217
	v_and_b32_e32 v251, 0xffff0000, v217
	v_max_f32_e32 v248, 0x1e3ce508, v248
	v_max_f32_e32 v249, 0x1e3ce508, v249
	v_max_f32_e32 v250, 0x1e3ce508, v250
	v_max_f32_e32 v251, 0x1e3ce508, v251
	v_rcp_f32_e32 v248, v248
	v_rcp_f32_e32 v249, v249
	v_rcp_f32_e32 v250, v250
	v_rcp_f32_e32 v251, v251
	v_lshlrev_b32_e32 v252, 16, v212
	v_and_b32_e32 v253, 0xffff0000, v212
	v_lshlrev_b32_e32 v254, 16, v213
	v_and_b32_e32 v255, 0xffff0000, v213
	v_pk_mul_f32 v[248:249], v[248:249], v[252:253]
	v_pk_mul_f32 v[250:251], v[250:251], v[254:255]
	v_pk_mul_f32 v[86:87], v[86:87], v[248:249]
	v_pk_mul_f32 v[88:89], v[88:89], v[250:251]
	global_load_dwordx4 v[210:213], v[36:37], off offset:-1792
	global_load_dwordx4 v[214:217], v[36:37], off offset:2304
	v_lshl_add_u64 v[36:37], v[36:37], 0, s[4:5]
	s_waitcnt vmcnt(14)
	v_lshlrev_b32_e32 v248, 16, v222
	v_and_b32_e32 v249, 0xffff0000, v222
	v_lshlrev_b32_e32 v250, 16, v223
	v_and_b32_e32 v251, 0xffff0000, v223
	v_max_f32_e32 v248, 0x1e3ce508, v248
	v_max_f32_e32 v249, 0x1e3ce508, v249
	v_max_f32_e32 v250, 0x1e3ce508, v250
	v_max_f32_e32 v251, 0x1e3ce508, v251
	v_rcp_f32_e32 v248, v248
	v_rcp_f32_e32 v249, v249
	v_rcp_f32_e32 v250, v250
	v_rcp_f32_e32 v251, v251
	v_lshlrev_b32_e32 v252, 16, v218
	v_and_b32_e32 v253, 0xffff0000, v218
	v_lshlrev_b32_e32 v254, 16, v219
	v_and_b32_e32 v255, 0xffff0000, v219
	v_pk_mul_f32 v[248:249], v[248:249], v[252:253]
	v_pk_mul_f32 v[250:251], v[250:251], v[254:255]
	v_pk_mul_f32 v[82:83], v[82:83], v[248:249]
	v_pk_mul_f32 v[84:85], v[84:85], v[250:251]
	v_lshlrev_b32_e32 v248, 16, v224
	v_and_b32_e32 v249, 0xffff0000, v224
	v_lshlrev_b32_e32 v250, 16, v225
	v_and_b32_e32 v251, 0xffff0000, v225
	v_max_f32_e32 v248, 0x1e3ce508, v248
	v_max_f32_e32 v249, 0x1e3ce508, v249
	v_max_f32_e32 v250, 0x1e3ce508, v250
	v_max_f32_e32 v251, 0x1e3ce508, v251
	v_rcp_f32_e32 v248, v248
	v_rcp_f32_e32 v249, v249
	v_rcp_f32_e32 v250, v250
	v_rcp_f32_e32 v251, v251
	v_lshlrev_b32_e32 v252, 16, v220
	v_and_b32_e32 v253, 0xffff0000, v220
	v_lshlrev_b32_e32 v254, 16, v221
	v_and_b32_e32 v255, 0xffff0000, v221
	v_pk_mul_f32 v[248:249], v[248:249], v[252:253]
	v_pk_mul_f32 v[250:251], v[250:251], v[254:255]
	v_pk_mul_f32 v[78:79], v[78:79], v[248:249]
	v_pk_mul_f32 v[80:81], v[80:81], v[250:251]
	global_load_dwordx4 v[218:221], v[36:37], off offset:-2048
	global_load_dwordx4 v[222:225], v[36:37], off offset:2048
	s_waitcnt vmcnt(14)
	v_lshlrev_b32_e32 v248, 16, v230
	v_and_b32_e32 v249, 0xffff0000, v230
	v_lshlrev_b32_e32 v250, 16, v231
	v_and_b32_e32 v251, 0xffff0000, v231
	v_max_f32_e32 v248, 0x1e3ce508, v248
	v_max_f32_e32 v249, 0x1e3ce508, v249
	v_max_f32_e32 v250, 0x1e3ce508, v250
	v_max_f32_e32 v251, 0x1e3ce508, v251
	v_rcp_f32_e32 v248, v248
	v_rcp_f32_e32 v249, v249
	v_rcp_f32_e32 v250, v250
	v_rcp_f32_e32 v251, v251
	v_lshlrev_b32_e32 v252, 16, v226
	v_and_b32_e32 v253, 0xffff0000, v226
	v_lshlrev_b32_e32 v254, 16, v227
	v_and_b32_e32 v255, 0xffff0000, v227
	v_pk_mul_f32 v[248:249], v[248:249], v[252:253]
	v_pk_mul_f32 v[250:251], v[250:251], v[254:255]
	v_pk_mul_f32 v[74:75], v[74:75], v[248:249]
	v_pk_mul_f32 v[76:77], v[76:77], v[250:251]
	v_lshlrev_b32_e32 v248, 16, v232
	v_and_b32_e32 v249, 0xffff0000, v232
	v_lshlrev_b32_e32 v250, 16, v233
	v_and_b32_e32 v251, 0xffff0000, v233
	v_max_f32_e32 v248, 0x1e3ce508, v248
	v_max_f32_e32 v249, 0x1e3ce508, v249
	v_max_f32_e32 v250, 0x1e3ce508, v250
	v_max_f32_e32 v251, 0x1e3ce508, v251
	v_rcp_f32_e32 v248, v248
	v_rcp_f32_e32 v249, v249
	v_rcp_f32_e32 v250, v250
	v_rcp_f32_e32 v251, v251
	v_lshlrev_b32_e32 v252, 16, v228
	v_and_b32_e32 v253, 0xffff0000, v228
	v_lshlrev_b32_e32 v254, 16, v229
	v_and_b32_e32 v255, 0xffff0000, v229
	v_pk_mul_f32 v[248:249], v[248:249], v[252:253]
	v_pk_mul_f32 v[250:251], v[250:251], v[254:255]
	v_pk_mul_f32 v[70:71], v[70:71], v[248:249]
	v_pk_mul_f32 v[72:73], v[72:73], v[250:251]
	global_load_dwordx4 v[226:229], v[36:37], off offset:-1792
	global_load_dwordx4 v[230:233], v[36:37], off offset:2304
	v_lshl_add_u64 v[36:37], v[36:37], 0, s[4:5]
	s_waitcnt vmcnt(14)
; __device__ __forceinline__ float fast_rcp(float x) { return __builtin_amdgcn_rcpf(x); }
;     __device__ __forceinline__ void mid(f32x4 (&acc)[2][2][4][2], const Unit& u, int wr, int wc, int fr, int fq, int t) const {
;     ...
;                     const u32x4 gn = *(const u32x4*)(gp + bj * 128), gd = *(const u32x4*)(gp + bj * 128 + 2048);
;                     f32x4 r0, r1;
;                     r0[0] = bflo(gn.x) * fast_rcp(fmaxf(bflo(gd.x), 1e-20f)); r0[1] = bfhi(gn.x) * fast_rcp(fmaxf(bfhi(gd.x), 1e-20f));
;                     r0[2] = bflo(gn.y) * fast_rcp(fmaxf(bflo(gd.y), 1e-20f)); r0[3] = bfhi(gn.y) * fast_rcp(fmaxf(bfhi(gd.y), 1e-20f));
;                     r1[0] = bflo(gn.z) * fast_rcp(fmaxf(bflo(gd.z), 1e-20f)); r1[1] = bfhi(gn.z) * fast_rcp(fmaxf(bfhi(gd.z), 1e-20f));
;                     r1[2] = bflo(gn.w) * fast_rcp(fmaxf(bflo(gd.w), 1e-20f)); r1[3] = bfhi(gn.w) * fast_rcp(fmaxf(bfhi(gd.w), 1e-20f));
;                     acc[ai][bj][m][0] *= r0; acc[ai][bj][m][1] *= r1;
;                 }
;                 if (m == 1 || m == 3) __builtin_amdgcn_sched_barrier(0);
	v_lshlrev_b32_e32 v248, 16, v138
	v_and_b32_e32 v249, 0xffff0000, v138
	v_lshlrev_b32_e32 v250, 16, v139
	v_and_b32_e32 v251, 0xffff0000, v139
	v_max_f32_e32 v248, 0x1e3ce508, v248
	v_max_f32_e32 v249, 0x1e3ce508, v249
	v_max_f32_e32 v250, 0x1e3ce508, v250
	v_max_f32_e32 v251, 0x1e3ce508, v251
	v_rcp_f32_e32 v248, v248
	v_rcp_f32_e32 v249, v249
	v_rcp_f32_e32 v250, v250
	v_rcp_f32_e32 v251, v251
	v_lshlrev_b32_e32 v252, 16, v134
	v_and_b32_e32 v253, 0xffff0000, v134
	v_lshlrev_b32_e32 v254, 16, v135
	v_and_b32_e32 v255, 0xffff0000, v135
	v_pk_mul_f32 v[248:249], v[248:249], v[252:253]
	v_pk_mul_f32 v[250:251], v[250:251], v[254:255]
	v_pk_mul_f32 v[66:67], v[66:67], v[248:249]
	v_pk_mul_f32 v[68:69], v[68:69], v[250:251]
	v_lshlrev_b32_e32 v248, 16, v140
	v_and_b32_e32 v249, 0xffff0000, v140
	v_lshlrev_b32_e32 v250, 16, v141
	v_and_b32_e32 v251, 0xffff0000, v141
	v_max_f32_e32 v248, 0x1e3ce508, v248
	v_max_f32_e32 v249, 0x1e3ce508, v249
	v_max_f32_e32 v250, 0x1e3ce508, v250
	v_max_f32_e32 v251, 0x1e3ce508, v251
	v_rcp_f32_e32 v248, v248
	v_rcp_f32_e32 v249, v249
	v_rcp_f32_e32 v250, v250
	v_rcp_f32_e32 v251, v251
	v_lshlrev_b32_e32 v252, 16, v136
	v_and_b32_e32 v253, 0xffff0000, v136
	v_lshlrev_b32_e32 v254, 16, v137
	v_and_b32_e32 v255, 0xffff0000, v137
	v_pk_mul_f32 v[248:249], v[248:249], v[252:253]
	v_pk_mul_f32 v[250:251], v[250:251], v[254:255]
	v_pk_mul_f32 v[62:63], v[62:63], v[248:249]
	v_pk_mul_f32 v[64:65], v[64:65], v[250:251]
	s_waitcnt vmcnt(12)
	v_lshlrev_b32_e32 v248, 16, v182
	v_and_b32_e32 v249, 0xffff0000, v182
	v_lshlrev_b32_e32 v250, 16, v183
	v_and_b32_e32 v251, 0xffff0000, v183
	v_max_f32_e32 v248, 0x1e3ce508, v248
	v_max_f32_e32 v249, 0x1e3ce508, v249
	v_max_f32_e32 v250, 0x1e3ce508, v250
	v_max_f32_e32 v251, 0x1e3ce508, v251
	v_rcp_f32_e32 v248, v248
	v_rcp_f32_e32 v249, v249
	v_rcp_f32_e32 v250, v250
	v_rcp_f32_e32 v251, v251
	v_lshlrev_b32_e32 v252, 16, v178
	v_and_b32_e32 v253, 0xffff0000, v178
	v_lshlrev_b32_e32 v254, 16, v179
	v_and_b32_e32 v255, 0xffff0000, v179
	v_pk_mul_f32 v[248:249], v[248:249], v[252:253]
	v_pk_mul_f32 v[250:251], v[250:251], v[254:255]
	v_pk_mul_f32 v[58:59], v[58:59], v[248:249]
	v_pk_mul_f32 v[60:61], v[60:61], v[250:251]
	v_lshlrev_b32_e32 v248, 16, v184
	v_and_b32_e32 v249, 0xffff0000, v184
	v_lshlrev_b32_e32 v250, 16, v185
	v_and_b32_e32 v251, 0xffff0000, v185
	v_max_f32_e32 v248, 0x1e3ce508, v248
	v_max_f32_e32 v249, 0x1e3ce508, v249
	v_max_f32_e32 v250, 0x1e3ce508, v250
	v_max_f32_e32 v251, 0x1e3ce508, v251
	v_rcp_f32_e32 v248, v248
	v_rcp_f32_e32 v249, v249
	v_rcp_f32_e32 v250, v250
	v_rcp_f32_e32 v251, v251
	v_lshlrev_b32_e32 v252, 16, v180
	v_and_b32_e32 v253, 0xffff0000, v180
	v_lshlrev_b32_e32 v254, 16, v181
	v_and_b32_e32 v255, 0xffff0000, v181
	v_pk_mul_f32 v[248:249], v[248:249], v[252:253]
	v_pk_mul_f32 v[250:251], v[250:251], v[254:255]
	v_pk_mul_f32 v[54:55], v[54:55], v[248:249]
	v_pk_mul_f32 v[56:57], v[56:57], v[250:251]
	s_waitcnt vmcnt(10)
	v_lshlrev_b32_e32 v248, 16, v190
	v_and_b32_e32 v249, 0xffff0000, v190
	v_lshlrev_b32_e32 v250, 16, v191
	v_and_b32_e32 v251, 0xffff0000, v191
	v_max_f32_e32 v248, 0x1e3ce508, v248
	v_max_f32_e32 v249, 0x1e3ce508, v249
	v_max_f32_e32 v250, 0x1e3ce508, v250
	v_max_f32_e32 v251, 0x1e3ce508, v251
	v_rcp_f32_e32 v248, v248
	v_rcp_f32_e32 v249, v249
	v_rcp_f32_e32 v250, v250
	v_rcp_f32_e32 v251, v251
	v_lshlrev_b32_e32 v252, 16, v186
	v_and_b32_e32 v253, 0xffff0000, v186
	v_lshlrev_b32_e32 v254, 16, v187
	v_and_b32_e32 v255, 0xffff0000, v187
	v_pk_mul_f32 v[248:249], v[248:249], v[252:253]
	v_pk_mul_f32 v[250:251], v[250:251], v[254:255]
	v_pk_mul_f32 v[50:51], v[50:51], v[248:249]
	v_pk_mul_f32 v[52:53], v[52:53], v[250:251]
	v_lshlrev_b32_e32 v248, 16, v192
	v_and_b32_e32 v249, 0xffff0000, v192
	v_lshlrev_b32_e32 v250, 16, v193
	v_and_b32_e32 v251, 0xffff0000, v193
	v_max_f32_e32 v248, 0x1e3ce508, v248
	v_max_f32_e32 v249, 0x1e3ce508, v249
	v_max_f32_e32 v250, 0x1e3ce508, v250
	v_max_f32_e32 v251, 0x1e3ce508, v251
	v_rcp_f32_e32 v248, v248
	v_rcp_f32_e32 v249, v249
	v_rcp_f32_e32 v250, v250
	v_rcp_f32_e32 v251, v251
	v_lshlrev_b32_e32 v252, 16, v188
	v_and_b32_e32 v253, 0xffff0000, v188
	v_lshlrev_b32_e32 v254, 16, v189
	v_and_b32_e32 v255, 0xffff0000, v189
	v_pk_mul_f32 v[248:249], v[248:249], v[252:253]
	v_pk_mul_f32 v[250:251], v[250:251], v[254:255]
	v_pk_mul_f32 v[46:47], v[46:47], v[248:249]
	v_pk_mul_f32 v[48:49], v[48:49], v[250:251]
	s_waitcnt vmcnt(8)
	v_lshlrev_b32_e32 v248, 16, v198
	v_and_b32_e32 v249, 0xffff0000, v198
	v_lshlrev_b32_e32 v250, 16, v199
	v_and_b32_e32 v251, 0xffff0000, v199
	v_max_f32_e32 v248, 0x1e3ce508, v248
	v_max_f32_e32 v249, 0x1e3ce508, v249
	v_max_f32_e32 v250, 0x1e3ce508, v250
	v_max_f32_e32 v251, 0x1e3ce508, v251
	v_rcp_f32_e32 v248, v248
	v_rcp_f32_e32 v249, v249
	v_rcp_f32_e32 v250, v250
	v_rcp_f32_e32 v251, v251
	v_lshlrev_b32_e32 v252, 16, v194
	v_and_b32_e32 v253, 0xffff0000, v194
	v_lshlrev_b32_e32 v254, 16, v195
	v_and_b32_e32 v255, 0xffff0000, v195
	v_pk_mul_f32 v[248:249], v[248:249], v[252:253]
	v_pk_mul_f32 v[250:251], v[250:251], v[254:255]
	v_pk_mul_f32 v[42:43], v[42:43], v[248:249]
	v_pk_mul_f32 v[44:45], v[44:45], v[250:251]
	v_lshlrev_b32_e32 v248, 16, v200
	v_and_b32_e32 v249, 0xffff0000, v200
	v_lshlrev_b32_e32 v250, 16, v201
	v_and_b32_e32 v251, 0xffff0000, v201
	v_max_f32_e32 v248, 0x1e3ce508, v248
	v_max_f32_e32 v249, 0x1e3ce508, v249
	v_max_f32_e32 v250, 0x1e3ce508, v250
	v_max_f32_e32 v251, 0x1e3ce508, v251
	v_rcp_f32_e32 v248, v248
	v_rcp_f32_e32 v249, v249
	v_rcp_f32_e32 v250, v250
	v_rcp_f32_e32 v251, v251
	v_lshlrev_b32_e32 v252, 16, v196
	v_and_b32_e32 v253, 0xffff0000, v196
	v_lshlrev_b32_e32 v254, 16, v197
	v_and_b32_e32 v255, 0xffff0000, v197
	v_pk_mul_f32 v[248:249], v[248:249], v[252:253]
	v_pk_mul_f32 v[250:251], v[250:251], v[254:255]
	v_pk_mul_f32 v[38:39], v[38:39], v[248:249]
	v_pk_mul_f32 v[40:41], v[40:41], v[250:251]
	s_waitcnt vmcnt(6)
; __device__ __forceinline__ float fast_rcp(float x) { return __builtin_amdgcn_rcpf(x); }
;     __device__ __forceinline__ void mid(f32x4 (&acc)[2][2][4][2], const Unit& u, int wr, int wc, int fr, int fq, int t) const {
;     ...
;                     const u32x4 gn = *(const u32x4*)(gp + bj * 128), gd = *(const u32x4*)(gp + bj * 128 + 2048);
;                     f32x4 r0, r1;
;                     r0[0] = bflo(gn.x) * fast_rcp(fmaxf(bflo(gd.x), 1e-20f)); r0[1] = bfhi(gn.x) * fast_rcp(fmaxf(bfhi(gd.x), 1e-20f));
;                     r0[2] = bflo(gn.y) * fast_rcp(fmaxf(bflo(gd.y), 1e-20f)); r0[3] = bfhi(gn.y) * fast_rcp(fmaxf(bfhi(gd.y), 1e-20f));
;                     r1[0] = bflo(gn.z) * fast_rcp(fmaxf(bflo(gd.z), 1e-20f)); r1[1] = bfhi(gn.z) * fast_rcp(fmaxf(bfhi(gd.z), 1e-20f));
;                     r1[2] = bflo(gn.w) * fast_rcp(fmaxf(bflo(gd.w), 1e-20f)); r1[3] = bfhi(gn.w) * fast_rcp(fmaxf(bfhi(gd.w), 1e-20f));
;                     acc[ai][bj][m][0] *= r0; acc[ai][bj][m][1] *= r1;
;                 }
;                 if (m == 1 || m == 3) __builtin_amdgcn_sched_barrier(0);
	v_lshlrev_b32_e32 v248, 16, v206
	v_and_b32_e32 v249, 0xffff0000, v206
	v_lshlrev_b32_e32 v250, 16, v207
	v_and_b32_e32 v251, 0xffff0000, v207
	v_max_f32_e32 v248, 0x1e3ce508, v248
	v_max_f32_e32 v249, 0x1e3ce508, v249
	v_max_f32_e32 v250, 0x1e3ce508, v250
	v_max_f32_e32 v251, 0x1e3ce508, v251
	v_rcp_f32_e32 v248, v248
	v_rcp_f32_e32 v249, v249
	v_rcp_f32_e32 v250, v250
	v_rcp_f32_e32 v251, v251
	v_lshlrev_b32_e32 v252, 16, v202
	v_and_b32_e32 v253, 0xffff0000, v202
	v_lshlrev_b32_e32 v254, 16, v203
	v_and_b32_e32 v255, 0xffff0000, v203
	v_pk_mul_f32 v[248:249], v[248:249], v[252:253]
	v_pk_mul_f32 v[250:251], v[250:251], v[254:255]
	v_pk_mul_f32 v[28:29], v[28:29], v[248:249]
	v_pk_mul_f32 v[30:31], v[30:31], v[250:251]
	v_lshlrev_b32_e32 v248, 16, v208
	v_and_b32_e32 v249, 0xffff0000, v208
	v_lshlrev_b32_e32 v250, 16, v209
	v_and_b32_e32 v251, 0xffff0000, v209
	v_max_f32_e32 v248, 0x1e3ce508, v248
	v_max_f32_e32 v249, 0x1e3ce508, v249
	v_max_f32_e32 v250, 0x1e3ce508, v250
	v_max_f32_e32 v251, 0x1e3ce508, v251
	v_rcp_f32_e32 v248, v248
	v_rcp_f32_e32 v249, v249
	v_rcp_f32_e32 v250, v250
	v_rcp_f32_e32 v251, v251
	v_lshlrev_b32_e32 v252, 16, v204
	v_and_b32_e32 v253, 0xffff0000, v204
	v_lshlrev_b32_e32 v254, 16, v205
	v_and_b32_e32 v255, 0xffff0000, v205
	v_pk_mul_f32 v[248:249], v[248:249], v[252:253]
	v_pk_mul_f32 v[250:251], v[250:251], v[254:255]
	v_pk_mul_f32 v[24:25], v[24:25], v[248:249]
	v_pk_mul_f32 v[26:27], v[26:27], v[250:251]
	s_waitcnt vmcnt(4)
	v_lshlrev_b32_e32 v248, 16, v214
	v_and_b32_e32 v249, 0xffff0000, v214
	v_lshlrev_b32_e32 v250, 16, v215
	v_and_b32_e32 v251, 0xffff0000, v215
	v_max_f32_e32 v248, 0x1e3ce508, v248
	v_max_f32_e32 v249, 0x1e3ce508, v249
	v_max_f32_e32 v250, 0x1e3ce508, v250
	v_max_f32_e32 v251, 0x1e3ce508, v251
	v_rcp_f32_e32 v248, v248
	v_rcp_f32_e32 v249, v249
	v_rcp_f32_e32 v250, v250
	v_rcp_f32_e32 v251, v251
	v_lshlrev_b32_e32 v252, 16, v210
	v_and_b32_e32 v253, 0xffff0000, v210
	v_lshlrev_b32_e32 v254, 16, v211
	v_and_b32_e32 v255, 0xffff0000, v211
	v_pk_mul_f32 v[248:249], v[248:249], v[252:253]
	v_pk_mul_f32 v[250:251], v[250:251], v[254:255]
	v_pk_mul_f32 v[20:21], v[20:21], v[248:249]
	v_pk_mul_f32 v[22:23], v[22:23], v[250:251]
	v_lshlrev_b32_e32 v248, 16, v216
	v_and_b32_e32 v249, 0xffff0000, v216
	v_lshlrev_b32_e32 v250, 16, v217
	v_and_b32_e32 v251, 0xffff0000, v217
	v_max_f32_e32 v248, 0x1e3ce508, v248
	v_max_f32_e32 v249, 0x1e3ce508, v249
	v_max_f32_e32 v250, 0x1e3ce508, v250
	v_max_f32_e32 v251, 0x1e3ce508, v251
	v_rcp_f32_e32 v248, v248
	v_rcp_f32_e32 v249, v249
	v_rcp_f32_e32 v250, v250
	v_rcp_f32_e32 v251, v251
	v_lshlrev_b32_e32 v252, 16, v212
	v_and_b32_e32 v253, 0xffff0000, v212
	v_lshlrev_b32_e32 v254, 16, v213
	v_and_b32_e32 v255, 0xffff0000, v213
	v_pk_mul_f32 v[248:249], v[248:249], v[252:253]
	v_pk_mul_f32 v[250:251], v[250:251], v[254:255]
	v_pk_mul_f32 v[16:17], v[16:17], v[248:249]
	v_pk_mul_f32 v[18:19], v[18:19], v[250:251]
	s_waitcnt vmcnt(2)
	v_lshlrev_b32_e32 v248, 16, v222
	v_and_b32_e32 v249, 0xffff0000, v222
	v_lshlrev_b32_e32 v250, 16, v223
	v_and_b32_e32 v251, 0xffff0000, v223
	v_max_f32_e32 v248, 0x1e3ce508, v248
	v_max_f32_e32 v249, 0x1e3ce508, v249
	v_max_f32_e32 v250, 0x1e3ce508, v250
	v_max_f32_e32 v251, 0x1e3ce508, v251
	v_rcp_f32_e32 v248, v248
	v_rcp_f32_e32 v249, v249
	v_rcp_f32_e32 v250, v250
	v_rcp_f32_e32 v251, v251
	v_lshlrev_b32_e32 v252, 16, v218
	v_and_b32_e32 v253, 0xffff0000, v218
	v_lshlrev_b32_e32 v254, 16, v219
	v_and_b32_e32 v255, 0xffff0000, v219
	v_pk_mul_f32 v[248:249], v[248:249], v[252:253]
	v_pk_mul_f32 v[250:251], v[250:251], v[254:255]
	v_pk_mul_f32 v[12:13], v[12:13], v[248:249]
	v_pk_mul_f32 v[14:15], v[14:15], v[250:251]
	v_lshlrev_b32_e32 v248, 16, v224
	v_and_b32_e32 v249, 0xffff0000, v224
	v_lshlrev_b32_e32 v250, 16, v225
	v_and_b32_e32 v251, 0xffff0000, v225
	v_max_f32_e32 v248, 0x1e3ce508, v248
	v_max_f32_e32 v249, 0x1e3ce508, v249
	v_max_f32_e32 v250, 0x1e3ce508, v250
	v_max_f32_e32 v251, 0x1e3ce508, v251
	v_rcp_f32_e32 v248, v248
	v_rcp_f32_e32 v249, v249
	v_rcp_f32_e32 v250, v250
	v_rcp_f32_e32 v251, v251
	v_lshlrev_b32_e32 v252, 16, v220
	v_and_b32_e32 v253, 0xffff0000, v220
	v_lshlrev_b32_e32 v254, 16, v221
	v_and_b32_e32 v255, 0xffff0000, v221
	v_pk_mul_f32 v[248:249], v[248:249], v[252:253]
	v_pk_mul_f32 v[250:251], v[250:251], v[254:255]
	v_pk_mul_f32 v[8:9], v[8:9], v[248:249]
	v_pk_mul_f32 v[10:11], v[10:11], v[250:251]
	s_waitcnt vmcnt(0)
	v_lshlrev_b32_e32 v248, 16, v230
	v_and_b32_e32 v249, 0xffff0000, v230
	v_lshlrev_b32_e32 v250, 16, v231
	v_and_b32_e32 v251, 0xffff0000, v231
	v_max_f32_e32 v248, 0x1e3ce508, v248
	v_max_f32_e32 v249, 0x1e3ce508, v249
	v_max_f32_e32 v250, 0x1e3ce508, v250
	v_max_f32_e32 v251, 0x1e3ce508, v251
	v_rcp_f32_e32 v248, v248
	v_rcp_f32_e32 v249, v249
	v_rcp_f32_e32 v250, v250
	v_rcp_f32_e32 v251, v251
	v_lshlrev_b32_e32 v252, 16, v226
	v_and_b32_e32 v253, 0xffff0000, v226
	v_lshlrev_b32_e32 v254, 16, v227
	v_and_b32_e32 v255, 0xffff0000, v227
	v_pk_mul_f32 v[248:249], v[248:249], v[252:253]
	v_pk_mul_f32 v[250:251], v[250:251], v[254:255]
	v_pk_mul_f32 v[4:5], v[4:5], v[248:249]
	v_pk_mul_f32 v[6:7], v[6:7], v[250:251]
	v_lshlrev_b32_e32 v248, 16, v232
	v_and_b32_e32 v249, 0xffff0000, v232
	v_lshlrev_b32_e32 v250, 16, v233
	v_and_b32_e32 v251, 0xffff0000, v233
	v_max_f32_e32 v248, 0x1e3ce508, v248
	v_max_f32_e32 v249, 0x1e3ce508, v249
	v_max_f32_e32 v250, 0x1e3ce508, v250
	v_max_f32_e32 v251, 0x1e3ce508, v251
	v_rcp_f32_e32 v248, v248
	v_rcp_f32_e32 v249, v249
	v_rcp_f32_e32 v250, v250
	v_rcp_f32_e32 v251, v251
	v_lshlrev_b32_e32 v252, 16, v228
	v_and_b32_e32 v253, 0xffff0000, v228
	v_lshlrev_b32_e32 v254, 16, v229
	v_and_b32_e32 v255, 0xffff0000, v229
	v_pk_mul_f32 v[248:249], v[248:249], v[252:253]
	v_pk_mul_f32 v[250:251], v[250:251], v[254:255]
	v_pk_mul_f32 v[0:1], v[0:1], v[248:249]
	v_pk_mul_f32 v[2:3], v[2:3], v[250:251]

; __device__ __forceinline__ unsigned pk2(float lo, float hi) { f32x2 v = {lo, hi}; bf16x2_t b = __builtin_convertvector(v, bf16x2_t); return __builtin_bit_cast(unsigned, b); }
;     __device__ __forceinline__ void operator()(const f32x4 (&acc)[2][2][4][2], const Unit& u, int wr, int wc, int fr, int fq) const {
;         const int row0 = u.pm * 256 + wr * 64 + fr, col0 = u.pn * 256 + wc * 32 + 8 * fq;
; #pragma unroll
;         for (int ai = 0; ai < 2; ++ai)
; #pragma unroll
;             for (int m = 0; m < 4; ++m) {
;                 const size_t row = (size_t)(row0 + ai * 128 + m * 16);
; #pragma unroll
;                 for (int bj = 0; bj < 2; ++bj) {
;                     const int col = col0 + bj * 128;
;                     const u32x4 g = *(const u32x4*)(P + row * PS + C_GATE + 4096 + col);
;                     f32x4 v0 = acc[ai][bj][m][0], v1 = acc[ai][bj][m][1];
;                     v0[0] *= fmaxf(bflo(g.x), 1e-20f); v0[1] *= fmaxf(bfhi(g.x), 1e-20f); v0[2] *= fmaxf(bflo(g.y), 1e-20f); v0[3] *= fmaxf(bfhi(g.y), 1e-20f);
;                     v1[0] *= fmaxf(bflo(g.z), 1e-20f); v1[1] *= fmaxf(bfhi(g.z), 1e-20f); v1[2] *= fmaxf(bflo(g.w), 1e-20f); v1[3] *= fmaxf(bfhi(g.w), 1e-20f);
;                     u32x4 w; w.x = pk2(v0[0], v0[1]); w.y = pk2(v0[2], v0[3]); w.z = pk2(v1[0], v1[1]); w.w = pk2(v1[2], v1[3]);
;                     *(u32x4*)(Yb + row * DM + col) = w;
.LBB0_795:
	v_lshl_add_u32 v34, s18, 8, v174
	v_mov_b64_e32 v[36:37], s[40:41]
	v_ashrrev_i32_e32 v159, 31, v158
	v_mad_i64_i32 v[36:37], vcc, v34, s90, v[36:37]
	v_lshlrev_b64 v[160:161], 1, v[158:159]
	v_lshl_add_u64 v[36:37], v[36:37], 0, s[36:37]
	v_mov_b32_e32 v164, v34
	v_ashrrev_i32_e32 v165, 31, v34
	v_lshl_add_u64 v[36:37], v[36:37], 0, v[160:161]
	v_lshlrev_b64 v[164:165], 12, v[164:165]
	v_lshl_add_u64 v[162:163], s[42:43], 0, v[164:165]
	v_lshl_add_u64 v[162:163], v[162:163], 0, v[160:161]
	s_mov_b32 s4, 0x60000
	s_mov_b32 s5, 0
	global_load_dwordx4 v[134:137], v[36:37], off
	global_load_dwordx4 v[138:141], v[36:37], off offset:256
	v_lshl_add_u64 v[36:37], v[36:37], 0, s[4:5]
	global_load_dwordx4 v[178:181], v[36:37], off
	global_load_dwordx4 v[182:185], v[36:37], off offset:256
	v_lshl_add_u64 v[36:37], v[36:37], 0, s[4:5]
	global_load_dwordx4 v[186:189], v[36:37], off
	global_load_dwordx4 v[190:193], v[36:37], off offset:256
	v_lshl_add_u64 v[36:37], v[36:37], 0, s[4:5]
	global_load_dwordx4 v[194:197], v[36:37], off
	global_load_dwordx4 v[198:201], v[36:37], off offset:256
	s_mov_b32 s4, 0x1e0000
	v_lshl_add_u64 v[36:37], v[36:37], 0, s[4:5]
	s_mov_b32 s4, 0x60000
	global_load_dwordx4 v[202:205], v[36:37], off
	global_load_dwordx4 v[206:209], v[36:37], off offset:256
	v_lshl_add_u64 v[36:37], v[36:37], 0, s[4:5]
	global_load_dwordx4 v[210:213], v[36:37], off
	global_load_dwordx4 v[214:217], v[36:37], off offset:256
	v_lshl_add_u64 v[36:37], v[36:37], 0, s[4:5]
	global_load_dwordx4 v[218:221], v[36:37], off
	global_load_dwordx4 v[222:225], v[36:37], off offset:256
	v_lshl_add_u64 v[36:37], v[36:37], 0, s[4:5]
	global_load_dwordx4 v[226:229], v[36:37], off
	global_load_dwordx4 v[230:233], v[36:37], off offset:256
	s_mov_b32 s4, 0x10000
	s_waitcnt vmcnt(15)
	v_lshlrev_b32_e32 v248, 16, v134
	v_and_b32_e32 v249, 0xffff0000, v134
	v_lshlrev_b32_e32 v250, 16, v135
	v_and_b32_e32 v251, 0xffff0000, v135
	v_max_f32_e32 v248, 0x1e3ce508, v248
	v_max_f32_e32 v249, 0x1e3ce508, v249
	v_max_f32_e32 v250, 0x1e3ce508, v250
	v_max_f32_e32 v251, 0x1e3ce508, v251
	v_pk_mul_f32 v[130:131], v[130:131], v[248:249]
	v_pk_mul_f32 v[132:133], v[132:133], v[250:251]
	v_lshlrev_b32_e32 v248, 16, v136
	v_and_b32_e32 v249, 0xffff0000, v136
	v_lshlrev_b32_e32 v250, 16, v137
	v_and_b32_e32 v251, 0xffff0000, v137
	v_max_f32_e32 v248, 0x1e3ce508, v248
	v_max_f32_e32 v249, 0x1e3ce508, v249
	v_max_f32_e32 v250, 0x1e3ce508, v250
	v_max_f32_e32 v251, 0x1e3ce508, v251
	v_pk_mul_f32 v[126:127], v[126:127], v[248:249]
	v_pk_mul_f32 v[128:129], v[128:129], v[250:251]
	v_cvt_pk_bf16_f32 v134, v130, v131
	v_cvt_pk_bf16_f32 v135, v132, v133
	v_cvt_pk_bf16_f32 v136, v126, v127
	v_cvt_pk_bf16_f32 v137, v128, v129
	global_store_dwordx4 v[162:163], v[134:137], off
	s_waitcnt vmcnt(15)
	v_lshlrev_b32_e32 v248, 16, v138
	v_and_b32_e32 v249, 0xffff0000, v138
	v_lshlrev_b32_e32 v250, 16, v139
	v_and_b32_e32 v251, 0xffff0000, v139
	v_max_f32_e32 v248, 0x1e3ce508, v248
	v_max_f32_e32 v249, 0x1e3ce508, v249
	v_max_f32_e32 v250, 0x1e3ce508, v250
	v_max_f32_e32 v251, 0x1e3ce508, v251
	v_pk_mul_f32 v[122:123], v[122:123], v[248:249]
	v_pk_mul_f32 v[124:125], v[124:125], v[250:251]
	v_lshlrev_b32_e32 v248, 16, v140
	v_and_b32_e32 v249, 0xffff0000, v140
	v_lshlrev_b32_e32 v250, 16, v141
	v_and_b32_e32 v251, 0xffff0000, v141
	v_max_f32_e32 v248, 0x1e3ce508, v248
	v_max_f32_e32 v249, 0x1e3ce508, v249
	v_max_f32_e32 v250, 0x1e3ce508, v250
	v_max_f32_e32 v251, 0x1e3ce508, v251
	v_pk_mul_f32 v[118:119], v[118:119], v[248:249]
	v_pk_mul_f32 v[120:121], v[120:121], v[250:251]
	v_cvt_pk_bf16_f32 v138, v122, v123
	v_cvt_pk_bf16_f32 v139, v124, v125
	v_cvt_pk_bf16_f32 v140, v118, v119
	v_cvt_pk_bf16_f32 v141, v120, v121
	global_store_dwordx4 v[162:163], v[138:141], off offset:256
	v_lshl_add_u64 v[162:163], v[162:163], 0, s[4:5]
	s_waitcnt vmcnt(15)
	v_lshlrev_b32_e32 v248, 16, v178
	v_and_b32_e32 v249, 0xffff0000, v178
	v_lshlrev_b32_e32 v250, 16, v179
	v_and_b32_e32 v251, 0xffff0000, v179
	v_max_f32_e32 v248, 0x1e3ce508, v248
	v_max_f32_e32 v249, 0x1e3ce508, v249
	v_max_f32_e32 v250, 0x1e3ce508, v250
	v_max_f32_e32 v251, 0x1e3ce508, v251
	v_pk_mul_f32 v[114:115], v[114:115], v[248:249]
	v_pk_mul_f32 v[116:117], v[116:117], v[250:251]
	v_lshlrev_b32_e32 v248, 16, v180
	v_and_b32_e32 v249, 0xffff0000, v180
	v_lshlrev_b32_e32 v250, 16, v181
	v_and_b32_e32 v251, 0xffff0000, v181
	v_max_f32_e32 v248, 0x1e3ce508, v248
	v_max_f32_e32 v249, 0x1e3ce508, v249
	v_max_f32_e32 v250, 0x1e3ce508, v250
	v_max_f32_e32 v251, 0x1e3ce508, v251
	v_pk_mul_f32 v[110:111], v[110:111], v[248:249]
	v_pk_mul_f32 v[112:113], v[112:113], v[250:251]
	v_cvt_pk_bf16_f32 v178, v114, v115
	v_cvt_pk_bf16_f32 v179, v116, v117
	v_cvt_pk_bf16_f32 v180, v110, v111
	v_cvt_pk_bf16_f32 v181, v112, v113
	global_store_dwordx4 v[162:163], v[178:181], off
	s_waitcnt vmcnt(15)
	v_lshlrev_b32_e32 v248, 16, v182
	v_and_b32_e32 v249, 0xffff0000, v182
	v_lshlrev_b32_e32 v250, 16, v183
	v_and_b32_e32 v251, 0xffff0000, v183
	v_max_f32_e32 v248, 0x1e3ce508, v248
	v_max_f32_e32 v249, 0x1e3ce508, v249
	v_max_f32_e32 v250, 0x1e3ce508, v250
	v_max_f32_e32 v251, 0x1e3ce508, v251
	v_pk_mul_f32 v[106:107], v[106:107], v[248:249]
	v_pk_mul_f32 v[108:109], v[108:109], v[250:251]
	v_lshlrev_b32_e32 v248, 16, v184
	v_and_b32_e32 v249, 0xffff0000, v184
	v_lshlrev_b32_e32 v250, 16, v185
	v_and_b32_e32 v251, 0xffff0000, v185
	v_max_f32_e32 v248, 0x1e3ce508, v248
	v_max_f32_e32 v249, 0x1e3ce508, v249
	v_max_f32_e32 v250, 0x1e3ce508, v250
	v_max_f32_e32 v251, 0x1e3ce508, v251
	v_pk_mul_f32 v[102:103], v[102:103], v[248:249]
	v_pk_mul_f32 v[104:105], v[104:105], v[250:251]
	v_cvt_pk_bf16_f32 v182, v106, v107
	v_cvt_pk_bf16_f32 v183, v108, v109
	v_cvt_pk_bf16_f32 v184, v102, v103
	v_cvt_pk_bf16_f32 v185, v104, v105
	global_store_dwordx4 v[162:163], v[182:185], off offset:256
	v_lshl_add_u64 v[162:163], v[162:163], 0, s[4:5]
	s_waitcnt vmcnt(15)
; __device__ __forceinline__ unsigned pk2(float lo, float hi) { f32x2 v = {lo, hi}; bf16x2_t b = __builtin_convertvector(v, bf16x2_t); return __builtin_bit_cast(unsigned, b); }
;     __device__ __forceinline__ void operator()(const f32x4 (&acc)[2][2][4][2], const Unit& u, int wr, int wc, int fr, int fq) const {
;     ...
;                 const size_t row = (size_t)(row0 + ai * 128 + m * 16);
; #pragma unroll
;                 for (int bj = 0; bj < 2; ++bj) {
;                     const int col = col0 + bj * 128;
;                     const u32x4 g = *(const u32x4*)(P + row * PS + C_GATE + 4096 + col);
;                     f32x4 v0 = acc[ai][bj][m][0], v1 = acc[ai][bj][m][1];
;                     v0[0] *= fmaxf(bflo(g.x), 1e-20f); v0[1] *= fmaxf(bfhi(g.x), 1e-20f); v0[2] *= fmaxf(bflo(g.y), 1e-20f); v0[3] *= fmaxf(bfhi(g.y), 1e-20f);
;                     v1[0] *= fmaxf(bflo(g.z), 1e-20f); v1[1] *= fmaxf(bfhi(g.z), 1e-20f); v1[2] *= fmaxf(bflo(g.w), 1e-20f); v1[3] *= fmaxf(bfhi(g.w), 1e-20f);
;                     u32x4 w; w.x = pk2(v0[0], v0[1]); w.y = pk2(v0[2], v0[3]); w.z = pk2(v1[0], v1[1]); w.w = pk2(v1[2], v1[3]);
;                     *(u32x4*)(Yb + row * DM + col) = w;
	v_lshlrev_b32_e32 v248, 16, v186
	v_and_b32_e32 v249, 0xffff0000, v186
	v_lshlrev_b32_e32 v250, 16, v187
	v_and_b32_e32 v251, 0xffff0000, v187
	v_max_f32_e32 v248, 0x1e3ce508, v248
	v_max_f32_e32 v249, 0x1e3ce508, v249
	v_max_f32_e32 v250, 0x1e3ce508, v250
	v_max_f32_e32 v251, 0x1e3ce508, v251
	v_pk_mul_f32 v[98:99], v[98:99], v[248:249]
	v_pk_mul_f32 v[100:101], v[100:101], v[250:251]
	v_lshlrev_b32_e32 v248, 16, v188
	v_and_b32_e32 v249, 0xffff0000, v188
	v_lshlrev_b32_e32 v250, 16, v189
	v_and_b32_e32 v251, 0xffff0000, v189
	v_max_f32_e32 v248, 0x1e3ce508, v248
	v_max_f32_e32 v249, 0x1e3ce508, v249
	v_max_f32_e32 v250, 0x1e3ce508, v250
	v_max_f32_e32 v251, 0x1e3ce508, v251
	v_pk_mul_f32 v[94:95], v[94:95], v[248:249]
	v_pk_mul_f32 v[96:97], v[96:97], v[250:251]
	v_cvt_pk_bf16_f32 v186, v98, v99
	v_cvt_pk_bf16_f32 v187, v100, v101
	v_cvt_pk_bf16_f32 v188, v94, v95
	v_cvt_pk_bf16_f32 v189, v96, v97
	global_store_dwordx4 v[162:163], v[186:189], off
	s_waitcnt vmcnt(15)
	v_lshlrev_b32_e32 v248, 16, v190
	v_and_b32_e32 v249, 0xffff0000, v190
	v_lshlrev_b32_e32 v250, 16, v191
	v_and_b32_e32 v251, 0xffff0000, v191
	v_max_f32_e32 v248, 0x1e3ce508, v248
	v_max_f32_e32 v249, 0x1e3ce508, v249
	v_max_f32_e32 v250, 0x1e3ce508, v250
	v_max_f32_e32 v251, 0x1e3ce508, v251
	v_pk_mul_f32 v[90:91], v[90:91], v[248:249]
	v_pk_mul_f32 v[92:93], v[92:93], v[250:251]
	v_lshlrev_b32_e32 v248, 16, v192
	v_and_b32_e32 v249, 0xffff0000, v192
	v_lshlrev_b32_e32 v250, 16, v193
	v_and_b32_e32 v251, 0xffff0000, v193
	v_max_f32_e32 v248, 0x1e3ce508, v248
	v_max_f32_e32 v249, 0x1e3ce508, v249
	v_max_f32_e32 v250, 0x1e3ce508, v250
	v_max_f32_e32 v251, 0x1e3ce508, v251
	v_pk_mul_f32 v[86:87], v[86:87], v[248:249]
	v_pk_mul_f32 v[88:89], v[88:89], v[250:251]
	v_cvt_pk_bf16_f32 v190, v90, v91
	v_cvt_pk_bf16_f32 v191, v92, v93
	v_cvt_pk_bf16_f32 v192, v86, v87
	v_cvt_pk_bf16_f32 v193, v88, v89
	global_store_dwordx4 v[162:163], v[190:193], off offset:256
	v_lshl_add_u64 v[162:163], v[162:163], 0, s[4:5]
	s_waitcnt vmcnt(15)
	v_lshlrev_b32_e32 v248, 16, v194
	v_and_b32_e32 v249, 0xffff0000, v194
	v_lshlrev_b32_e32 v250, 16, v195
	v_and_b32_e32 v251, 0xffff0000, v195
	v_max_f32_e32 v248, 0x1e3ce508, v248
	v_max_f32_e32 v249, 0x1e3ce508, v249
	v_max_f32_e32 v250, 0x1e3ce508, v250
	v_max_f32_e32 v251, 0x1e3ce508, v251
	v_pk_mul_f32 v[82:83], v[82:83], v[248:249]
	v_pk_mul_f32 v[84:85], v[84:85], v[250:251]
	v_lshlrev_b32_e32 v248, 16, v196
	v_and_b32_e32 v249, 0xffff0000, v196
	v_lshlrev_b32_e32 v250, 16, v197
	v_and_b32_e32 v251, 0xffff0000, v197
	v_max_f32_e32 v248, 0x1e3ce508, v248
	v_max_f32_e32 v249, 0x1e3ce508, v249
	v_max_f32_e32 v250, 0x1e3ce508, v250
	v_max_f32_e32 v251, 0x1e3ce508, v251
	v_pk_mul_f32 v[78:79], v[78:79], v[248:249]
	v_pk_mul_f32 v[80:81], v[80:81], v[250:251]
	v_cvt_pk_bf16_f32 v194, v82, v83
	v_cvt_pk_bf16_f32 v195, v84, v85
	v_cvt_pk_bf16_f32 v196, v78, v79
	v_cvt_pk_bf16_f32 v197, v80, v81
	global_store_dwordx4 v[162:163], v[194:197], off
	s_waitcnt vmcnt(15)
	v_lshlrev_b32_e32 v248, 16, v198
	v_and_b32_e32 v249, 0xffff0000, v198
	v_lshlrev_b32_e32 v250, 16, v199
	v_and_b32_e32 v251, 0xffff0000, v199
	v_max_f32_e32 v248, 0x1e3ce508, v248
	v_max_f32_e32 v249, 0x1e3ce508, v249
	v_max_f32_e32 v250, 0x1e3ce508, v250
	v_max_f32_e32 v251, 0x1e3ce508, v251
	v_pk_mul_f32 v[74:75], v[74:75], v[248:249]
	v_pk_mul_f32 v[76:77], v[76:77], v[250:251]
	v_lshlrev_b32_e32 v248, 16, v200
	v_and_b32_e32 v249, 0xffff0000, v200
	v_lshlrev_b32_e32 v250, 16, v201
	v_and_b32_e32 v251, 0xffff0000, v201
	v_max_f32_e32 v248, 0x1e3ce508, v248
	v_max_f32_e32 v249, 0x1e3ce508, v249
	v_max_f32_e32 v250, 0x1e3ce508, v250
	v_max_f32_e32 v251, 0x1e3ce508, v251
	v_pk_mul_f32 v[70:71], v[70:71], v[248:249]
	v_pk_mul_f32 v[72:73], v[72:73], v[250:251]
	v_cvt_pk_bf16_f32 v198, v74, v75
	v_cvt_pk_bf16_f32 v199, v76, v77
	v_cvt_pk_bf16_f32 v200, v70, v71
	v_cvt_pk_bf16_f32 v201, v72, v73
	global_store_dwordx4 v[162:163], v[198:201], off offset:256
	s_mov_b32 s4, 0x50000
	v_lshl_add_u64 v[162:163], v[162:163], 0, s[4:5]
	s_mov_b32 s4, 0x10000
	s_waitcnt vmcnt(15)
	v_lshlrev_b32_e32 v248, 16, v202
	v_and_b32_e32 v249, 0xffff0000, v202
	v_lshlrev_b32_e32 v250, 16, v203
	v_and_b32_e32 v251, 0xffff0000, v203
	v_max_f32_e32 v248, 0x1e3ce508, v248
	v_max_f32_e32 v249, 0x1e3ce508, v249
	v_max_f32_e32 v250, 0x1e3ce508, v250
	v_max_f32_e32 v251, 0x1e3ce508, v251
	v_pk_mul_f32 v[66:67], v[66:67], v[248:249]
	v_pk_mul_f32 v[68:69], v[68:69], v[250:251]
	v_lshlrev_b32_e32 v248, 16, v204
	v_and_b32_e32 v249, 0xffff0000, v204
	v_lshlrev_b32_e32 v250, 16, v205
	v_and_b32_e32 v251, 0xffff0000, v205
	v_max_f32_e32 v248, 0x1e3ce508, v248
	v_max_f32_e32 v249, 0x1e3ce508, v249
	v_max_f32_e32 v250, 0x1e3ce508, v250
	v_max_f32_e32 v251, 0x1e3ce508, v251
	v_pk_mul_f32 v[62:63], v[62:63], v[248:249]
	v_pk_mul_f32 v[64:65], v[64:65], v[250:251]
	v_cvt_pk_bf16_f32 v202, v66, v67
	v_cvt_pk_bf16_f32 v203, v68, v69
	v_cvt_pk_bf16_f32 v204, v62, v63
	v_cvt_pk_bf16_f32 v205, v64, v65
	global_store_dwordx4 v[162:163], v[202:205], off
	s_waitcnt vmcnt(15)
	v_lshlrev_b32_e32 v248, 16, v206
	v_and_b32_e32 v249, 0xffff0000, v206
	v_lshlrev_b32_e32 v250, 16, v207
	v_and_b32_e32 v251, 0xffff0000, v207
	v_max_f32_e32 v248, 0x1e3ce508, v248
	v_max_f32_e32 v249, 0x1e3ce508, v249
	v_max_f32_e32 v250, 0x1e3ce508, v250
	v_max_f32_e32 v251, 0x1e3ce508, v251
	v_pk_mul_f32 v[58:59], v[58:59], v[248:249]
	v_pk_mul_f32 v[60:61], v[60:61], v[250:251]
	v_lshlrev_b32_e32 v248, 16, v208
	v_and_b32_e32 v249, 0xffff0000, v208
	v_lshlrev_b32_e32 v250, 16, v209
	v_and_b32_e32 v251, 0xffff0000, v209
	v_max_f32_e32 v248, 0x1e3ce508, v248
	v_max_f32_e32 v249, 0x1e3ce508, v249
	v_max_f32_e32 v250, 0x1e3ce508, v250
	v_max_f32_e32 v251, 0x1e3ce508, v251
	v_pk_mul_f32 v[54:55], v[54:55], v[248:249]
	v_pk_mul_f32 v[56:57], v[56:57], v[250:251]
	v_cvt_pk_bf16_f32 v206, v58, v59
	v_cvt_pk_bf16_f32 v207, v60, v61
	v_cvt_pk_bf16_f32 v208, v54, v55
	v_cvt_pk_bf16_f32 v209, v56, v57
	global_store_dwordx4 v[162:163], v[206:209], off offset:256
	v_lshl_add_u64 v[162:163], v[162:163], 0, s[4:5]
	s_waitcnt vmcnt(15)
; __device__ __forceinline__ unsigned pk2(float lo, float hi) { f32x2 v = {lo, hi}; bf16x2_t b = __builtin_convertvector(v, bf16x2_t); return __builtin_bit_cast(unsigned, b); }
;     __device__ __forceinline__ void operator()(const f32x4 (&acc)[2][2][4][2], const Unit& u, int wr, int wc, int fr, int fq) const {
;     ...
;                 const size_t row = (size_t)(row0 + ai * 128 + m * 16);
; #pragma unroll
;                 for (int bj = 0; bj < 2; ++bj) {
;                     const int col = col0 + bj * 128;
;                     const u32x4 g = *(const u32x4*)(P + row * PS + C_GATE + 4096 + col);
;                     f32x4 v0 = acc[ai][bj][m][0], v1 = acc[ai][bj][m][1];
;                     v0[0] *= fmaxf(bflo(g.x), 1e-20f); v0[1] *= fmaxf(bfhi(g.x), 1e-20f); v0[2] *= fmaxf(bflo(g.y), 1e-20f); v0[3] *= fmaxf(bfhi(g.y), 1e-20f);
;                     v1[0] *= fmaxf(bflo(g.z), 1e-20f); v1[1] *= fmaxf(bfhi(g.z), 1e-20f); v1[2] *= fmaxf(bflo(g.w), 1e-20f); v1[3] *= fmaxf(bfhi(g.w), 1e-20f);
;                     u32x4 w; w.x = pk2(v0[0], v0[1]); w.y = pk2(v0[2], v0[3]); w.z = pk2(v1[0], v1[1]); w.w = pk2(v1[2], v1[3]);
;                     *(u32x4*)(Yb + row * DM + col) = w;
	v_lshlrev_b32_e32 v248, 16, v210
	v_and_b32_e32 v249, 0xffff0000, v210
	v_lshlrev_b32_e32 v250, 16, v211
	v_and_b32_e32 v251, 0xffff0000, v211
	v_max_f32_e32 v248, 0x1e3ce508, v248
	v_max_f32_e32 v249, 0x1e3ce508, v249
	v_max_f32_e32 v250, 0x1e3ce508, v250
	v_max_f32_e32 v251, 0x1e3ce508, v251
	v_pk_mul_f32 v[50:51], v[50:51], v[248:249]
	v_pk_mul_f32 v[52:53], v[52:53], v[250:251]
	v_lshlrev_b32_e32 v248, 16, v212
	v_and_b32_e32 v249, 0xffff0000, v212
	v_lshlrev_b32_e32 v250, 16, v213
	v_and_b32_e32 v251, 0xffff0000, v213
	v_max_f32_e32 v248, 0x1e3ce508, v248
	v_max_f32_e32 v249, 0x1e3ce508, v249
	v_max_f32_e32 v250, 0x1e3ce508, v250
	v_max_f32_e32 v251, 0x1e3ce508, v251
	v_pk_mul_f32 v[46:47], v[46:47], v[248:249]
	v_pk_mul_f32 v[48:49], v[48:49], v[250:251]
	v_cvt_pk_bf16_f32 v210, v50, v51
	v_cvt_pk_bf16_f32 v211, v52, v53
	v_cvt_pk_bf16_f32 v212, v46, v47
	v_cvt_pk_bf16_f32 v213, v48, v49
	global_store_dwordx4 v[162:163], v[210:213], off
	s_waitcnt vmcnt(15)
	v_lshlrev_b32_e32 v248, 16, v214
	v_and_b32_e32 v249, 0xffff0000, v214
	v_lshlrev_b32_e32 v250, 16, v215
	v_and_b32_e32 v251, 0xffff0000, v215
	v_max_f32_e32 v248, 0x1e3ce508, v248
	v_max_f32_e32 v249, 0x1e3ce508, v249
	v_max_f32_e32 v250, 0x1e3ce508, v250
	v_max_f32_e32 v251, 0x1e3ce508, v251
	v_pk_mul_f32 v[42:43], v[42:43], v[248:249]
	v_pk_mul_f32 v[44:45], v[44:45], v[250:251]
	v_lshlrev_b32_e32 v248, 16, v216
	v_and_b32_e32 v249, 0xffff0000, v216
	v_lshlrev_b32_e32 v250, 16, v217
	v_and_b32_e32 v251, 0xffff0000, v217
	v_max_f32_e32 v248, 0x1e3ce508, v248
	v_max_f32_e32 v249, 0x1e3ce508, v249
	v_max_f32_e32 v250, 0x1e3ce508, v250
	v_max_f32_e32 v251, 0x1e3ce508, v251
	v_pk_mul_f32 v[38:39], v[38:39], v[248:249]
	v_pk_mul_f32 v[40:41], v[40:41], v[250:251]
	v_cvt_pk_bf16_f32 v214, v42, v43
	v_cvt_pk_bf16_f32 v215, v44, v45
	v_cvt_pk_bf16_f32 v216, v38, v39
	v_cvt_pk_bf16_f32 v217, v40, v41
	global_store_dwordx4 v[162:163], v[214:217], off offset:256
	v_lshl_add_u64 v[162:163], v[162:163], 0, s[4:5]
	s_waitcnt vmcnt(15)
	v_lshlrev_b32_e32 v248, 16, v218
	v_and_b32_e32 v249, 0xffff0000, v218
	v_lshlrev_b32_e32 v250, 16, v219
	v_and_b32_e32 v251, 0xffff0000, v219
	v_max_f32_e32 v248, 0x1e3ce508, v248
	v_max_f32_e32 v249, 0x1e3ce508, v249
	v_max_f32_e32 v250, 0x1e3ce508, v250
	v_max_f32_e32 v251, 0x1e3ce508, v251
	v_pk_mul_f32 v[28:29], v[28:29], v[248:249]
	v_pk_mul_f32 v[30:31], v[30:31], v[250:251]
	v_lshlrev_b32_e32 v248, 16, v220
	v_and_b32_e32 v249, 0xffff0000, v220
	v_lshlrev_b32_e32 v250, 16, v221
	v_and_b32_e32 v251, 0xffff0000, v221
	v_max_f32_e32 v248, 0x1e3ce508, v248
	v_max_f32_e32 v249, 0x1e3ce508, v249
	v_max_f32_e32 v250, 0x1e3ce508, v250
	v_max_f32_e32 v251, 0x1e3ce508, v251
	v_pk_mul_f32 v[24:25], v[24:25], v[248:249]
	v_pk_mul_f32 v[26:27], v[26:27], v[250:251]
	v_cvt_pk_bf16_f32 v218, v28, v29
	v_cvt_pk_bf16_f32 v219, v30, v31
	v_cvt_pk_bf16_f32 v220, v24, v25
	v_cvt_pk_bf16_f32 v221, v26, v27
	global_store_dwordx4 v[162:163], v[218:221], off
	s_waitcnt vmcnt(15)
	v_lshlrev_b32_e32 v248, 16, v222
	v_and_b32_e32 v249, 0xffff0000, v222
	v_lshlrev_b32_e32 v250, 16, v223
	v_and_b32_e32 v251, 0xffff0000, v223
	v_max_f32_e32 v248, 0x1e3ce508, v248
	v_max_f32_e32 v249, 0x1e3ce508, v249
	v_max_f32_e32 v250, 0x1e3ce508, v250
	v_max_f32_e32 v251, 0x1e3ce508, v251
	v_pk_mul_f32 v[20:21], v[20:21], v[248:249]
	v_pk_mul_f32 v[22:23], v[22:23], v[250:251]
	v_lshlrev_b32_e32 v248, 16, v224
	v_and_b32_e32 v249, 0xffff0000, v224
	v_lshlrev_b32_e32 v250, 16, v225
	v_and_b32_e32 v251, 0xffff0000, v225
	v_max_f32_e32 v248, 0x1e3ce508, v248
	v_max_f32_e32 v249, 0x1e3ce508, v249
	v_max_f32_e32 v250, 0x1e3ce508, v250
	v_max_f32_e32 v251, 0x1e3ce508, v251
	v_pk_mul_f32 v[16:17], v[16:17], v[248:249]
	v_pk_mul_f32 v[18:19], v[18:19], v[250:251]
	v_cvt_pk_bf16_f32 v222, v20, v21
	v_cvt_pk_bf16_f32 v223, v22, v23
	v_cvt_pk_bf16_f32 v224, v16, v17
	v_cvt_pk_bf16_f32 v225, v18, v19
	global_store_dwordx4 v[162:163], v[222:225], off offset:256
	v_lshl_add_u64 v[162:163], v[162:163], 0, s[4:5]
	s_waitcnt vmcnt(15)
	v_lshlrev_b32_e32 v248, 16, v226
	v_and_b32_e32 v249, 0xffff0000, v226
	v_lshlrev_b32_e32 v250, 16, v227
	v_and_b32_e32 v251, 0xffff0000, v227
	v_max_f32_e32 v248, 0x1e3ce508, v248
	v_max_f32_e32 v249, 0x1e3ce508, v249
	v_max_f32_e32 v250, 0x1e3ce508, v250
	v_max_f32_e32 v251, 0x1e3ce508, v251
	v_pk_mul_f32 v[12:13], v[12:13], v[248:249]
	v_pk_mul_f32 v[14:15], v[14:15], v[250:251]
	v_lshlrev_b32_e32 v248, 16, v228
	v_and_b32_e32 v249, 0xffff0000, v228
	v_lshlrev_b32_e32 v250, 16, v229
	v_and_b32_e32 v251, 0xffff0000, v229
	v_max_f32_e32 v248, 0x1e3ce508, v248
	v_max_f32_e32 v249, 0x1e3ce508, v249
	v_max_f32_e32 v250, 0x1e3ce508, v250
	v_max_f32_e32 v251, 0x1e3ce508, v251
	v_pk_mul_f32 v[8:9], v[8:9], v[248:249]
	v_pk_mul_f32 v[10:11], v[10:11], v[250:251]
	v_cvt_pk_bf16_f32 v226, v12, v13
	v_cvt_pk_bf16_f32 v227, v14, v15
	v_cvt_pk_bf16_f32 v228, v8, v9
	v_cvt_pk_bf16_f32 v229, v10, v11
	global_store_dwordx4 v[162:163], v[226:229], off
	s_waitcnt vmcnt(15)
	v_lshlrev_b32_e32 v248, 16, v230
	v_and_b32_e32 v249, 0xffff0000, v230
	v_lshlrev_b32_e32 v250, 16, v231
	v_and_b32_e32 v251, 0xffff0000, v231
	v_max_f32_e32 v248, 0x1e3ce508, v248
	v_max_f32_e32 v249, 0x1e3ce508, v249
	v_max_f32_e32 v250, 0x1e3ce508, v250
	v_max_f32_e32 v251, 0x1e3ce508, v251
	v_pk_mul_f32 v[4:5], v[4:5], v[248:249]
	v_pk_mul_f32 v[6:7], v[6:7], v[250:251]
	v_lshlrev_b32_e32 v248, 16, v232
	v_and_b32_e32 v249, 0xffff0000, v232
	v_lshlrev_b32_e32 v250, 16, v233
	v_and_b32_e32 v251, 0xffff0000, v233
	v_max_f32_e32 v248, 0x1e3ce508, v248
	v_max_f32_e32 v249, 0x1e3ce508, v249
	v_max_f32_e32 v250, 0x1e3ce508, v250
	v_max_f32_e32 v251, 0x1e3ce508, v251
	v_pk_mul_f32 v[0:1], v[0:1], v[248:249]
	v_pk_mul_f32 v[2:3], v[2:3], v[250:251]
	v_cvt_pk_bf16_f32 v230, v4, v5
	v_cvt_pk_bf16_f32 v231, v6, v7
	v_cvt_pk_bf16_f32 v232, v0, v1
	v_cvt_pk_bf16_f32 v233, v2, v3
	global_store_dwordx4 v[162:163], v[230:233], off offset:256
	s_andn2_b64 vcc, exec, s[56:57]
	s_mov_b64 s[0:1], -1
	s_cbranch_vccnz .LBB0_776
	s_andn2_b64 vcc, exec, s[38:39]
	s_cbranch_vccnz .LBB0_775
	s_barrier
	s_branch .LBB0_775
